# lane exchanges in chain loop and P4/P6 epilogues via permlane swap and dpp instead of ds_bpermute
# speedup vs baseline: 1.0420x; 1.0040x over previous
; #define LAS __attribute__((address_space(3)))
; __device__ __forceinline__ f32x4 mfma16(h16x8 a, h16x8 b, f32x4 c) { return __builtin_amdgcn_mfma_f32_16x16x32_f16(a, b, c, 0, 0, 0); }
; __device__ __forceinline__ float row_sum16(float x) { x = dpp_add<0xB1>(x); x = dpp_add<0x4E>(x); x = dpp_add<0x124>(x); x = dpp_add<0x128>(x); return x; }
; __device__ __forceinline__ void mlstm_chain(const Params& p, LAS unsigned char* lds, const MlChain ch) {
;     ...
;         {
;             const int tt = wave & 3, sp = wave >> 2;
;             h16x8 qa[2];
; #pragma unroll
;             for (int ks = 0; ks < 2; ++ks) qa[ks] = *(const LAS h16x8*)(QS + (tt * 16 + fr) * 72 + ks * 32 + fq * 8);
;             float mx[4];
; #pragma unroll
;             for (int r = 0; r < 4; ++r) mx[r] = fmaxf(mcur, CCM[c * 64 + tt * 16 + fq * 4 + r]);
;             float dpart[4] = {0.f, 0.f, 0.f, 0.f};
; #pragma unroll
;             for (int j = 0; j < 2; ++j) {
;                 const int st = sp * 2 + j;
;                 f32x4 acc = {0.f, 0.f, 0.f, 0.f};
; #pragma unroll
;                 for (int ks = 0; ks < 2; ++ks) { const h16x8 kb = *(const LAS h16x8*)(KS + (st * 16 + fr) * 72 + ks * 32 + fq * 8); acc = mfma16(qa[ks], kb, acc); }
;                 const int s = st * 16 + fr; const float us = CUU[c * 64 + s];
; #pragma unroll
;                 for (int r = 0; r < 4; ++r) {
;                     const int t = tt * 16 + fq * 4 + r;
;                     const float wgt = (s <= t) ? __expf(us - mx[r]) : 0.f;
;                     const float pv = acc[r] * wgt; dpart[r] += pv; PP[t * 72 + s] = (h16)pv;
;                 }
;             }
; #pragma unroll
;             for (int r = 0; r < 4; ++r) {
;                 float d = dpart[r]; d = row_sum16(d);
;                 if (fr == 0) DEN[sp * 64 + tt * 16 + fq * 4 + r] = d;
;             }
;             const int t = tid >> 3, part = tid & 7;
;             const h16x8 q8 = *(const LAS h16x8*)(QS + t * 72 + part * 8);
;             const f32x4 n0 = *(const LAS f32x4*)(NL + part * 8), n1 = *(const LAS f32x4*)(NL + part * 8 + 4);
;             float a = 0.f;
; #pragma unroll
;             for (int j = 0; j < 4; ++j) a += (float)q8[j] * n0[j] + (float)q8[4 + j] * n1[j];
;             a = dpp_add<0xB1>(a); a = dpp_add<0x4E>(a); a += __shfl_xor(a, 4);
;             if (part == 0) DQN[t] = a;
.LBB0_234:
	s_or_b64 exec, exec, s[0:1]
	v_add_u32_e32 v72, 0, v202
	s_waitcnt lgkmcnt(0)
	s_barrier
	v_add_u32_e32 v72, 0x16600, v72
	ds_read_b128 v[72:75], v72
	v_add_u32_e32 v118, v188, v96
	ds_read_b128 v[76:79], v118 offset:18432
	ds_read_b128 v[84:87], v118 offset:18496
	ds_read_b128 v[88:91], v179 offset:27648
	v_max_f32_e32 v80, v99, v99
	v_add_u32_e32 v82, 0, v205
	s_waitcnt lgkmcnt(3)
	v_max_f32_e32 v72, v72, v72
	v_max_f32_e32 v119, v80, v72
	v_max_f32_e32 v72, v73, v73
	v_max_f32_e32 v124, v80, v72
	v_max_f32_e32 v72, v74, v74
	v_max_f32_e32 v125, v80, v72
	v_max_f32_e32 v81, v75, v75
	s_waitcnt lgkmcnt(0)
	v_mfma_f32_16x16x32_f16 v[72:75], v[76:79], v[88:91], 0
	v_add_u32_e32 v83, 0x14600, v82
	ds_read_b128 v[88:91], v179 offset:27712
	ds_read_b32 v120, v83
	v_max_f32_e32 v126, v80, v81
	v_add_u32_e32 v81, 0x14640, v82
	ds_read_b32 v127, v81
	s_waitcnt lgkmcnt(2)
	v_mfma_f32_16x16x32_f16 v[72:75], v[84:87], v[88:91], v[72:75]
	s_waitcnt lgkmcnt(1)
	v_sub_f32_e32 v81, v120, v119
	v_mul_f32_e32 v81, 0x3fb8aa3b, v81
	v_sub_f32_e32 v82, v120, v124
	v_exp_f32_e32 v81, v81
	v_mul_f32_e32 v82, 0x3fb8aa3b, v82
	v_exp_f32_e32 v82, v82
	v_cndmask_b32_e64 v148, v81, 0, s[26:27]
	v_fma_mixlo_f16 v81, v72, v148, 0
	v_cndmask_b32_e64 v83, v82, 0, s[28:29]
	ds_write_b16 v176, v81 offset:55296
	v_fma_mixlo_f16 v81, v73, v83, 0
	ds_write_b16 v176, v81 offset:55440
	v_sub_f32_e32 v81, v120, v125
	v_mul_f32_e32 v81, 0x3fb8aa3b, v81
	v_exp_f32_e32 v81, v81
	v_sub_f32_e32 v82, v120, v126
	v_mul_f32_e32 v82, 0x3fb8aa3b, v82
	v_exp_f32_e32 v88, v82
	v_cndmask_b32_e64 v82, v81, 0, s[24:25]
	v_fma_mixlo_f16 v81, v74, v82, 0
	ds_write_b16 v176, v81 offset:55584
	v_cndmask_b32_e64 v81, v88, 0, s[22:23]
	v_fma_mixlo_f16 v88, v75, v81, 0
	ds_write_b16 v176, v88 offset:55728
	ds_read_b128 v[88:91], v179 offset:29952
	ds_read_b128 v[120:123], v179 offset:30016
	s_waitcnt lgkmcnt(1)
	v_mfma_f32_16x16x32_f16 v[76:79], v[76:79], v[88:91], 0
	v_sub_f32_e32 v88, v127, v119
	v_mul_f32_e32 v88, 0x3fb8aa3b, v88
	v_exp_f32_e32 v88, v88
	s_waitcnt lgkmcnt(0)
	v_mfma_f32_16x16x32_f16 v[76:79], v[84:87], v[120:123], v[76:79]
	v_sub_f32_e32 v84, v127, v124
	v_mul_f32_e32 v84, 0x3fb8aa3b, v84
	v_exp_f32_e32 v84, v84
	v_fma_f32 v89, v72, v148, 0
	v_cndmask_b32_e64 v72, v88, 0, s[20:21]
	s_nop 2
	v_fmac_f32_e32 v89, v76, v72
	v_fma_mixlo_f16 v72, v76, v72, 0
	v_cndmask_b32_e64 v84, v84, 0, s[18:19]
	ds_write_b16 v176, v72 offset:55328
	v_fma_mixlo_f16 v72, v77, v84, 0
	ds_write_b16 v176, v72 offset:55472
	v_sub_f32_e32 v72, v127, v125
	v_mul_f32_e32 v72, 0x3fb8aa3b, v72
	v_exp_f32_e32 v72, v72
	v_sub_f32_e32 v76, v127, v126
	v_mul_f32_e32 v76, 0x3fb8aa3b, v76
	v_exp_f32_e32 v85, v76
	v_cndmask_b32_e64 v76, v72, 0, s[16:17]
	v_fma_mixlo_f16 v72, v78, v76, 0
	ds_write_b16 v176, v72 offset:55616
	v_cndmask_b32_e64 v72, v85, 0, s[14:15]
	v_fma_mixlo_f16 v85, v79, v72, 0
	ds_write_b16 v176, v85 offset:55760
	s_nop 0
	v_add_f32_dpp v85, v89, v89 quad_perm:[1,0,3,2] row_mask:0xf bank_mask:0xf bound_ctrl:1
	s_nop 1
	v_add_f32_dpp v85, v85, v85 quad_perm:[2,3,0,1] row_mask:0xf bank_mask:0xf bound_ctrl:1
	s_nop 1
	v_add_f32_dpp v85, v85, v85 row_ror:4 row_mask:0xf bank_mask:0xf bound_ctrl:1
	s_nop 1
	v_mov_b32_dpp v86, v85 row_ror:8 row_mask:0xf bank_mask:0xf bound_ctrl:1
	s_and_saveexec_b64 s[0:1], s[12:13]
	v_add_f32_e32 v85, v85, v86
	v_add_u32_e32 v86, v170, v96
	ds_write_b32 v86, v85
	s_or_b64 exec, exec, s[0:1]
	v_mul_f32_e32 v73, v73, v83
	v_mul_f32_e32 v77, v77, v84
	v_add_f32_e32 v73, 0, v73
	v_add_f32_e32 v73, v73, v77
	s_nop 1
	v_add_f32_dpp v73, v73, v73 quad_perm:[1,0,3,2] row_mask:0xf bank_mask:0xf bound_ctrl:1
	s_nop 1
	v_add_f32_dpp v73, v73, v73 quad_perm:[2,3,0,1] row_mask:0xf bank_mask:0xf bound_ctrl:1
	s_nop 1
	v_add_f32_dpp v73, v73, v73 row_ror:4 row_mask:0xf bank_mask:0xf bound_ctrl:1
	s_nop 1
	v_mov_b32_dpp v77, v73 row_ror:8 row_mask:0xf bank_mask:0xf bound_ctrl:1
	s_and_saveexec_b64 s[0:1], s[12:13]
	v_add_f32_e32 v73, v73, v77
	v_add_u32_e32 v77, v170, v96
	ds_write_b32 v77, v73 offset:4
	s_or_b64 exec, exec, s[0:1]
	v_mul_f32_e32 v73, v74, v82
	v_mul_f32_e32 v74, v78, v76
	v_add_f32_e32 v73, 0, v73
	v_add_f32_e32 v73, v73, v74
	s_nop 1
	v_add_f32_dpp v73, v73, v73 quad_perm:[1,0,3,2] row_mask:0xf bank_mask:0xf bound_ctrl:1
	s_nop 1
	v_add_f32_dpp v73, v73, v73 quad_perm:[2,3,0,1] row_mask:0xf bank_mask:0xf bound_ctrl:1
	s_nop 1
	v_add_f32_dpp v73, v73, v73 row_ror:4 row_mask:0xf bank_mask:0xf bound_ctrl:1
	s_nop 1
	v_mov_b32_dpp v74, v73 row_ror:8 row_mask:0xf bank_mask:0xf bound_ctrl:1
	s_and_saveexec_b64 s[0:1], s[12:13]
	v_add_f32_e32 v73, v73, v74
	v_add_u32_e32 v74, v170, v96
	ds_write_b32 v74, v73 offset:8
	s_or_b64 exec, exec, s[0:1]
	v_mul_f32_e32 v73, v75, v81
	v_mul_f32_e32 v72, v79, v72
	v_add_f32_e32 v73, 0, v73
	v_add_f32_e32 v72, v73, v72
	s_nop 1
	v_add_f32_dpp v72, v72, v72 quad_perm:[1,0,3,2] row_mask:0xf bank_mask:0xf bound_ctrl:1
	s_nop 1
	v_add_f32_dpp v72, v72, v72 quad_perm:[2,3,0,1] row_mask:0xf bank_mask:0xf bound_ctrl:1
	s_nop 1
	v_add_f32_dpp v72, v72, v72 row_ror:4 row_mask:0xf bank_mask:0xf bound_ctrl:1
	s_nop 1
	v_mov_b32_dpp v73, v72 row_ror:8 row_mask:0xf bank_mask:0xf bound_ctrl:1
	s_and_saveexec_b64 s[0:1], s[12:13]
	v_add_f32_e32 v72, v72, v73
	v_add_u32_e32 v73, v170, v96
	ds_write_b32 v73, v72 offset:12
	s_or_b64 exec, exec, s[0:1]
	ds_read_b128 v[72:75], v158 offset:18432
	ds_read_b128 v[76:79], v169
	ds_read_b128 v[82:85], v169 offset:16
	s_waitcnt lgkmcnt(2)
	v_cvt_f32_f16_e32 v81, v74
	v_cvt_f32_f16_sdwa v74, v74 dst_sel:DWORD dst_unused:UNUSED_PAD src0_sel:WORD_1
	v_cvt_f32_f16_e32 v86, v75
	v_cvt_f32_f16_sdwa v75, v75 dst_sel:DWORD dst_unused:UNUSED_PAD src0_sel:WORD_1
	s_waitcnt lgkmcnt(0)
	v_mul_f32_e32 v81, v82, v81
	v_mul_f32_e32 v74, v83, v74
	v_fma_mix_f32 v76, v76, v72, v81 op_sel_hi:[0,1,0]
	v_fma_mix_f32 v72, v77, v72, v74 op_sel:[0,1,0] op_sel_hi:[0,1,0]
	v_add_f32_e32 v74, 0, v76
	v_add_f32_e32 v72, v72, v74
	v_mul_f32_e32 v74, v84, v86
	v_fma_mix_f32 v74, v78, v73, v74 op_sel_hi:[0,1,0]
	v_add_f32_e32 v72, v74, v72
	v_mul_f32_e32 v74, v85, v75
	v_fma_mix_f32 v73, v79, v73, v74 op_sel:[0,1,0] op_sel_hi:[0,1,0]
	v_add_f32_e32 v72, v73, v72
	s_nop 1
	v_add_f32_dpp v72, v72, v72 quad_perm:[1,0,3,2] row_mask:0xf bank_mask:0xf bound_ctrl:1
	s_nop 1
	v_add_f32_dpp v72, v72, v72 quad_perm:[2,3,0,1] row_mask:0xf bank_mask:0xf bound_ctrl:1
	s_nop 1
	v_mov_b32_dpp v73, v72 row_half_mirror row_mask:0xf bank_mask:0xf bound_ctrl:1
	s_and_saveexec_b64 s[0:1], s[10:11]
	s_cbranch_execz .LBB0_244
	s_waitcnt lgkmcnt(0)
	v_add_f32_e32 v72, v72, v73
	ds_write_b32 v168, v72
; #define LAS __attribute__((address_space(3)))
; __device__ __forceinline__ f32x4 mfma16(h16x8 a, h16x8 b, f32x4 c) { return __builtin_amdgcn_mfma_f32_16x16x32_f16(a, b, c, 0, 0, 0); }
; __device__ __forceinline__ float sigm(float x) { return __builtin_amdgcn_rcpf(1.f + __expf(-x)); }
; __device__ __forceinline__ void mlstm_chain(const Params& p, LAS unsigned char* lds, const MlChain ch) {
;     ...
;         {
;             const int tt = wave & 3, vp = wave >> 2, t = tt * 16 + fr;
;             h16x8 pa[2], qa[2];
; #pragma unroll
;             for (int ks = 0; ks < 2; ++ks) { pa[ks] = *(const LAS h16x8*)(PP + t * 72 + ks * 32 + fq * 8); qa[ks] = *(const LAS h16x8*)(QS + t * 72 + ks * 32 + fq * 8); }
;             const float mxt = fmaxf(mcur, CCM[c * 64 + t]);
;             const float sc = __expf(mcur - mxt);
;             const float den = DEN[t] + DEN[64 + t] + sc * DQN[t];
;             const float inv = __builtin_amdgcn_rcpf(fmaxf(fabsf(den), __expf(-(CBC[c * 64 + t] + mxt))));
;             float hv[2][4], ssq = 0.f;
; #pragma unroll
;             for (int j = 0; j < 2; ++j) {
;                 const int vt = vp * 2 + j;
;                 f32x4 a1 = {0.f, 0.f, 0.f, 0.f}, a2 = {0.f, 0.f, 0.f, 0.f};
; #pragma unroll
;                 for (int ks = 0; ks < 2; ++ks) {
;                     const h16x8 vb = *(const LAS h16x8*)(VT + (vt * 16 + fr) * 72 + ks * 32 + fq * 8);
;                     const h16x8 cbf = *(const LAS h16x8*)(CT + (vt * 16 + fr) * 72 + ks * 32 + fq * 8);
;                     a1 = mfma16(vb, pa[ks], a1); a2 = mfma16(cbf, qa[ks], a2);
;                 }
;                 const h16x4 o4 = j == 0 ? oc0 : oc1;
; #pragma unroll
;                 for (int r = 0; r < 4; ++r) { const float hh = (a1[r] + sc * a2[r]) * inv * sigm((float)o4[r]); hv[j][r] = hh; ssq += hh * hh; }
;             }
;             ssq += __shfl_xor(ssq, 16); ssq += __shfl_xor(ssq, 32);
;             if (fq == 0) SSQ[vp * 64 + t] = ssq;
.LBB0_244:
	s_or_b64 exec, exec, s[0:1]
	v_add_u32_e32 v76, 0, v201
	s_waitcnt lgkmcnt(0)
	s_barrier
	v_add_u32_e32 v72, 0x16600, v76
	ds_read_b32 v77, v72
	s_waitcnt lgkmcnt(1)
	ds_read_b128 v[72:75], v171 offset:55296
	v_add_u32_e32 v76, 0x12600, v76
	ds_read_b128 v[82:85], v171 offset:18496
	ds_read_b32 v81, v76
	s_waitcnt lgkmcnt(3)
	v_max_f32_e32 v76, v77, v77
	v_max_f32_e32 v80, v80, v76
	v_sub_f32_e32 v76, v99, v80
	v_mul_f32_e32 v76, 0x3fb8aa3b, v76
	v_exp_f32_e32 v90, v76
	ds_read_b32 v91, v165
	ds_read_b32 v99, v166
	ds_read_b32 v119, v167
	ds_read_b128 v[76:79], v164 offset:36864
	ds_read_b128 v[86:89], v171 offset:18432
	ds_read_b128 v[120:123], v171 offset:55360
	s_waitcnt lgkmcnt(6)
	v_add_f32_e32 v80, v80, v81
	ds_read_b128 v[124:127], v164 offset:64512
	ds_read_b128 v[208:211], v164 offset:39232
	v_mul_f32_e32 v80, 0xbfb8aa3b, v80
	v_exp_f32_e32 v80, v80
	s_waitcnt lgkmcnt(6)
	v_add_f32_e32 v91, v91, v99
	ds_read_b128 v[152:155], v164 offset:36928
	ds_read_b128 v[216:219], v164 offset:39168
	ds_read_b128 v[212:215], v164 offset:64576
	s_waitcnt lgkmcnt(8)
	v_fmac_f32_e32 v91, v119, v90
	v_max_f32_e64 v80, |v91|, v80
	v_rcp_f32_e32 v156, v80
	s_waitcnt vmcnt(5)
	v_cvt_f32_f16_e32 v80, v114
	v_cvt_f32_f16_sdwa v81, v114 dst_sel:DWORD dst_unused:UNUSED_PAD src0_sel:WORD_1
	s_waitcnt lgkmcnt(7)
	v_mfma_f32_16x16x32_f16 v[76:79], v[76:79], v[72:75], 0
	v_cvt_f32_f16_sdwa v99, v115 dst_sel:DWORD dst_unused:UNUSED_PAD src0_sel:WORD_1
	v_mul_f32_e32 v80, 0xbfb8aa3b, v80
	v_mul_f32_e32 v81, 0xbfb8aa3b, v81
	s_waitcnt lgkmcnt(4)
	v_mfma_f32_16x16x32_f16 v[124:127], v[124:127], v[86:89], 0
	v_exp_f32_e32 v80, v80
	v_exp_f32_e32 v81, v81
	ds_read_b128 v[148:151], v147 offset:64
	s_waitcnt lgkmcnt(3)
	v_mfma_f32_16x16x32_f16 v[76:79], v[152:155], v[120:123], v[76:79]
	v_add_f32_e32 v80, 1.0, v80
	v_add_f32_e32 v81, 1.0, v81
	v_rcp_f32_e32 v80, v80
	s_waitcnt lgkmcnt(1)
	v_mfma_f32_16x16x32_f16 v[124:127], v[212:215], v[82:85], v[124:127]
	v_rcp_f32_e32 v81, v81
	ds_read_b128 v[152:155], v147
	v_mfma_f32_16x16x32_f16 v[212:215], v[216:219], v[72:75], 0
	s_waitcnt vmcnt(4)
	v_cvt_f32_f16_e32 v74, v112
	s_nop 2
	v_pk_fma_f32 v[76:77], v[90:91], v[124:125], v[76:77] op_sel_hi:[0,1,1]
	v_cvt_f32_f16_e32 v91, v115
	v_pk_mul_f32 v[76:77], v[156:157], v[76:77] op_sel_hi:[0,1]
	v_pk_mul_f32 v[76:77], v[80:81], v[76:77]
	v_mul_f32_e32 v81, 0xbfb8aa3b, v99
	v_mul_f32_e32 v80, 0xbfb8aa3b, v91
	v_exp_f32_e32 v80, v80
	v_exp_f32_e32 v81, v81
	v_pk_fma_f32 v[72:73], v[90:91], v[126:127], v[78:79] op_sel_hi:[0,1,1]
	v_pk_mul_f32 v[72:73], v[156:157], v[72:73] op_sel_hi:[0,1]
	v_add_f32_e32 v80, 1.0, v80
	v_add_f32_e32 v81, 1.0, v81
	v_rcp_f32_e32 v80, v80
	v_rcp_f32_e32 v81, v81
	v_cvt_f32_f16_sdwa v75, v112 dst_sel:DWORD dst_unused:UNUSED_PAD src0_sel:WORD_1
	v_mul_f32_e32 v74, 0xbfb8aa3b, v74
	v_exp_f32_e32 v74, v74
	v_pk_mul_f32 v[72:73], v[80:81], v[72:73]
	s_waitcnt lgkmcnt(0)
	v_mfma_f32_16x16x32_f16 v[78:81], v[152:155], v[86:89], 0
	v_mul_f32_e32 v75, 0xbfb8aa3b, v75
	v_exp_f32_e32 v75, v75
	v_add_f32_e32 v74, 1.0, v74
	v_mfma_f32_16x16x32_f16 v[78:81], v[148:151], v[82:85], v[78:81]
	v_cvt_f32_f16_e32 v82, v113
	v_cvt_f32_f16_sdwa v83, v113 dst_sel:DWORD dst_unused:UNUSED_PAD src0_sel:WORD_1
	v_add_f32_e32 v75, 1.0, v75
	v_mfma_f32_16x16x32_f16 v[86:89], v[208:211], v[120:123], v[212:215]
	v_mul_f32_e32 v82, 0xbfb8aa3b, v82
	v_mul_f32_e32 v83, 0xbfb8aa3b, v83
	v_rcp_f32_e32 v74, v74
	v_rcp_f32_e32 v75, v75
	v_exp_f32_e32 v82, v82
	v_exp_f32_e32 v83, v83
	s_nop 1
	v_pk_fma_f32 v[78:79], v[90:91], v[78:79], v[86:87] op_sel_hi:[0,1,1]
	v_pk_mul_f32 v[78:79], v[156:157], v[78:79] op_sel_hi:[0,1]
	v_pk_mul_f32 v[78:79], v[74:75], v[78:79]
	v_add_f32_e32 v74, 1.0, v82
	v_add_f32_e32 v75, 1.0, v83
	v_pk_mul_f32 v[114:115], v[76:77], v[76:77]
	v_rcp_f32_e32 v74, v74
	v_rcp_f32_e32 v75, v75
	v_pk_mul_f32 v[124:125], v[72:73], v[72:73]
	v_add_f32_e32 v84, v114, v115
	v_pk_fma_f32 v[80:81], v[90:91], v[80:81], v[88:89] op_sel_hi:[0,1,1]
	v_add_f32_e32 v84, v124, v84
	v_pk_mul_f32 v[82:83], v[78:79], v[78:79]
	v_pk_mul_f32 v[80:81], v[156:157], v[80:81] op_sel_hi:[0,1]
	v_add_f32_e32 v84, v125, v84
	v_pk_mul_f32 v[74:75], v[74:75], v[80:81]
	v_add_f32_e32 v82, v84, v82
	v_pk_mul_f32 v[80:81], v[74:75], v[74:75]
	v_add_f32_e32 v82, v83, v82
	v_add_f32_e32 v80, v80, v82
	v_add_f32_e32 v80, v81, v80
	v_mov_b32_e32 v81, v80
	s_nop 1
	v_permlane16_swap_b32 v80, v81
	s_waitcnt lgkmcnt(0)
	v_add_f32_e32 v80, v80, v81
	v_mov_b32_e32 v81, v80
	s_nop 1
	v_permlane32_swap_b32 v80, v81
	s_and_saveexec_b64 s[0:1], vcc
	s_cbranch_execz .LBB0_246
	s_waitcnt lgkmcnt(0)
	v_add_f32_e32 v80, v80, v81
	v_add_u32_e32 v81, v160, v161
	ds_write_b32 v81, v80
; #define LAS __attribute__((address_space(3)))
; __device__ __forceinline__ f32x4 mfma16(h16x8 a, h16x8 b, f32x4 c) { return __builtin_amdgcn_mfma_f32_16x16x32_f16(a, b, c, 0, 0, 0); }
; __device__ __forceinline__ void lds_barrier() { asm volatile("s_waitcnt lgkmcnt(0)\n\ts_barrier" ::: "memory"); }
; __device__ __forceinline__ void mlstm_chain(const Params& p, LAS unsigned char* lds, const MlChain ch) {
;     ...
;             lds_barrier();
;             const float rstd = rsqrtf((SSQ[t] + SSQ[64 + t]) * (1.f / 64.f) + EPS);
;             if (t < nv) {
; #pragma unroll
;                 for (int j = 0; j < 2; ++j) {
;                     const int v0 = h * 64 + (vp * 2 + j) * 16 + fq * 4;
;                     const f32x4 nw = nwv[j];
;                     f32x4 o;
; #pragma unroll
;                     for (int r = 0; r < 4; ++r) o[r] = hv[j][r] * rstd * nw[r];
;                     *(h16x4*)(MIX + (size_t)(rowbase + t0 + t) * D + v0) = pack4(o);
;                 }
;             }
;         }
;         {
; #pragma unroll
;             for (int j = 0; j < 2; ++j) {
;                 const int vt = (wave >> 2) * 2 + j;
;                 Cacc[j] *= dec;
; #pragma unroll
;                 for (int ks = 0; ks < 2; ++ks) {
;                     const h16x8 kwf = *(const LAS h16x8*)(KW + (kt * 16 + fr) * 72 + ks * 32 + fq * 8);
;                     const h16x8 vf = *(const LAS h16x8*)(VT + (vt * 16 + fr) * 72 + ks * 32 + fq * 8);
;                     Cacc[j] = mfma16(kwf, vf, Cacc[j]);
;                 }
;                 *(LAS h16x4*)(CT + (vt * 16 + fr) * 72 + kt * 16 + fq * 4) = pack4(Cacc[j]);
;             }
;             {
;                 const int kch = tid >> 3, part = tid & 7;
;                 const h16x8 x = *(const LAS h16x8*)(KW + kch * 72 + part * 8);
;                 float a = 0.f;
; #pragma unroll
;                 for (int j = 0; j < 8; ++j) a += (float)x[j];
;                 a = dpp_add<0xB1>(a); a = dpp_add<0x4E>(a); a += __shfl_xor(a, 4);
;                 if (part == 0) NL[kch] = dec * NL[kch] + a;
.LBB0_246:
	s_or_b64 exec, exec, s[0:1]
	s_waitcnt lgkmcnt(0)
	s_barrier
	ds_read_b32 v80, v160
	s_waitcnt lgkmcnt(1)
	ds_read_b32 v81, v162
	ds_read_b128 v[82:85], v159 offset:46080
	v_sub_f32_e32 v86, v117, v181
	v_add_u32_e32 v99, v191, v187
	v_ashrrev_i32_e32 v117, 31, v116
	s_waitcnt lgkmcnt(1)
	v_add_f32_e32 v80, v80, v81
	v_fmamk_f32 v80, v80, 0x3c800000, v206
	v_mul_f32_e32 v81, 0x4b800000, v80
	v_cmp_gt_f32_e64 s[0:1], s51, v80
	v_lshlrev_b64 v[124:125], 11, v[116:117]
	s_nop 0
	v_cndmask_b32_e64 v80, v80, v81, s[0:1]
	v_rsq_f32_e32 v81, v80
	v_mul_f32_e32 v80, 0x3fb8aa3b, v86
	v_exp_f32_e32 v80, v80
	v_mul_f32_e32 v86, 0x45800000, v81
	v_cndmask_b32_e64 v90, v81, v86, s[0:1]
	ds_read_b128 v[86:89], v99 offset:36864
	ds_read_b128 v[120:123], v159 offset:46144
	v_pk_mul_f32 v[54:55], v[54:55], v[80:81] op_sel_hi:[1,0]
	v_pk_mul_f32 v[52:53], v[52:53], v[80:81] op_sel_hi:[1,0]
	ds_read_b128 v[112:115], v99 offset:36928
	v_pk_mul_f32 v[50:51], v[50:51], v[80:81] op_sel_hi:[1,0]
	s_waitcnt lgkmcnt(2)
	v_mfma_f32_16x16x32_f16 v[52:55], v[82:85], v[86:89], v[52:55]
	v_mul_f32_e64 v48, v48, v80
	v_mul_f32_e64 v49, v49, v80
	v_pk_mul_f32 v[76:77], v[76:77], v[90:91] op_sel_hi:[1,0]
	v_pk_mul_f32 v[72:73], v[72:73], v[90:91] op_sel_hi:[1,0]
	s_waitcnt lgkmcnt(0)
	v_mfma_f32_16x16x32_f16 v[52:55], v[120:123], v[112:115], v[52:55]
	v_add_u32_e32 v113, v185, v187
	v_add_u32_e32 v112, v191, v192
	v_pk_mul_f32 v[76:77], v[4:5], v[76:77]
	v_pk_mul_f32 v[72:73], v[6:7], v[72:73]
	v_cvt_pk_f16_f32 v76, v76, v77
	s_nop 2
	v_cvt_pk_f16_f32 v87, v54, v55
	v_cvt_pk_f16_f32 v86, v52, v53
	ds_write_b64 v113, v[86:87] offset:64512
	ds_read_b128 v[86:89], v112 offset:36864
	ds_read_b128 v[114:117], v112 offset:36928
	s_waitcnt lgkmcnt(1)
	v_mfma_f32_16x16x32_f16 v[48:51], v[82:85], v[86:89], v[48:51]
	v_cvt_pk_f16_f32 v77, v72, v73
	v_lshl_add_u64 v[86:87], v[100:101], 0, v[124:125]
	global_store_dwordx2 v[86:87], v[76:77], off
	s_waitcnt lgkmcnt(0)
	v_mfma_f32_16x16x32_f16 v[48:51], v[120:123], v[114:117], v[48:51]
	v_add_u32_e32 v114, v185, v192
	v_pk_mul_f32 v[74:75], v[74:75], v[90:91] op_sel_hi:[1,0]
	s_nop 0
	v_pk_mul_f32 v[74:75], v[2:3], v[74:75]
	s_nop 3
	v_cvt_pk_f16_f32 v73, v50, v51
	v_cvt_pk_f16_f32 v72, v48, v49
	ds_write_b64 v114, v[72:73] offset:64512
	ds_read_b128 v[82:85], v158 offset:46080
	v_pk_mul_f32 v[72:73], v[78:79], v[90:91] op_sel_hi:[1,0]
	s_waitcnt lgkmcnt(0)
	v_cvt_f32_f16_e32 v77, v83
	v_pk_mul_f32 v[72:73], v[0:1], v[72:73]
	v_cvt_f32_f16_sdwa v78, v83 dst_sel:DWORD dst_unused:UNUSED_PAD src0_sel:WORD_1
	v_cvt_pk_f16_f32 v76, v72, v73
	v_cvt_f32_f16_e32 v72, v82
	v_cvt_f32_f16_sdwa v73, v82 dst_sel:DWORD dst_unused:UNUSED_PAD src0_sel:WORD_1
	v_cvt_f32_f16_sdwa v79, v85 dst_sel:DWORD dst_unused:UNUSED_PAD src0_sel:WORD_1
	v_add_f32_e32 v72, 0, v72
	v_add_f32_e32 v72, v72, v73
	v_cvt_f32_f16_e32 v73, v84
	v_add_f32_e32 v72, v72, v77
	v_cvt_f32_f16_sdwa v77, v84 dst_sel:DWORD dst_unused:UNUSED_PAD src0_sel:WORD_1
	v_add_f32_e32 v72, v72, v78
	v_cvt_f32_f16_e32 v78, v85
	v_add_f32_e32 v72, v72, v73
	v_add_f32_e32 v72, v72, v77
	v_cvt_pk_f16_f32 v77, v74, v75
	v_add_f32_e32 v72, v72, v78
	v_add_f32_e32 v72, v72, v79
	global_store_dwordx2 v[86:87], v[76:77], off offset:32
	s_nop 0
	v_add_f32_dpp v72, v72, v72 quad_perm:[1,0,3,2] row_mask:0xf bank_mask:0xf bound_ctrl:1
	s_nop 1
	v_add_f32_dpp v72, v72, v72 quad_perm:[2,3,0,1] row_mask:0xf bank_mask:0xf bound_ctrl:1
	s_nop 1
	v_mov_b32_dpp v73, v72 row_half_mirror row_mask:0xf bank_mask:0xf bound_ctrl:1
	s_and_saveexec_b64 s[0:1], s[10:11]
	s_cbranch_execz .LBB0_248
	ds_read_b32 v74, v145
	s_waitcnt lgkmcnt(1)
	v_add_f32_e32 v72, v72, v73
	s_waitcnt lgkmcnt(0)
	v_fmac_f32_e32 v72, v80, v74
	ds_write_b32 v145, v72

; #define LAS __attribute__((address_space(3)))
; __device__ __forceinline__ f32x4 mfma16(h16x8 a, h16x8 b, f32x4 c) { return __builtin_amdgcn_mfma_f32_16x16x32_f16(a, b, c, 0, 0, 0); }
; __device__ __forceinline__ float row_sum16(float x) { x = dpp_add<0xB1>(x); x = dpp_add<0x4E>(x); x = dpp_add<0x124>(x); x = dpp_add<0x128>(x); return x; }
; __device__ __forceinline__ void mlstm_chain(const Params& p, LAS unsigned char* lds, const MlChain ch) {
;     ...
;         {
;             const int tt = wave & 3, sp = wave >> 2;
;             h16x8 qa[2];
; #pragma unroll
;             for (int ks = 0; ks < 2; ++ks) qa[ks] = *(const LAS h16x8*)(QS + (tt * 16 + fr) * 72 + ks * 32 + fq * 8);
;             float mx[4];
; #pragma unroll
;             for (int r = 0; r < 4; ++r) mx[r] = fmaxf(mcur, CCM[c * 64 + tt * 16 + fq * 4 + r]);
;             float dpart[4] = {0.f, 0.f, 0.f, 0.f};
; #pragma unroll
;             for (int j = 0; j < 2; ++j) {
;                 const int st = sp * 2 + j;
;                 f32x4 acc = {0.f, 0.f, 0.f, 0.f};
; #pragma unroll
;                 for (int ks = 0; ks < 2; ++ks) { const h16x8 kb = *(const LAS h16x8*)(KS + (st * 16 + fr) * 72 + ks * 32 + fq * 8); acc = mfma16(qa[ks], kb, acc); }
;                 const int s = st * 16 + fr; const float us = CUU[c * 64 + s];
; #pragma unroll
;                 for (int r = 0; r < 4; ++r) {
;                     const int t = tt * 16 + fq * 4 + r;
;                     const float wgt = (s <= t) ? __expf(us - mx[r]) : 0.f;
;                     const float pv = acc[r] * wgt; dpart[r] += pv; PP[t * 72 + s] = (h16)pv;
;                 }
;             }
; #pragma unroll
;             for (int r = 0; r < 4; ++r) {
;                 float d = dpart[r]; d = row_sum16(d);
;                 if (fr == 0) DEN[sp * 64 + tt * 16 + fq * 4 + r] = d;
;             }
;             const int t = tid >> 3, part = tid & 7;
;             const h16x8 q8 = *(const LAS h16x8*)(QS + t * 72 + part * 8);
;             const f32x4 n0 = *(const LAS f32x4*)(NL + part * 8), n1 = *(const LAS f32x4*)(NL + part * 8 + 4);
;             float a = 0.f;
; #pragma unroll
;             for (int j = 0; j < 4; ++j) a += (float)q8[j] * n0[j] + (float)q8[4 + j] * n1[j];
;             a = dpp_add<0xB1>(a); a = dpp_add<0x4E>(a); a += __shfl_xor(a, 4);
;             if (part == 0) DQN[t] = a;
.LBB0_268:
	s_or_b64 exec, exec, s[0:1]
	s_add_i32 s0, 0, 0x16600
	v_add3_u32 v8, s0, v172, v96
	s_add_i32 s0, 0, 0x16500
	s_waitcnt lgkmcnt(0)
	s_barrier
	v_lshl_add_u32 v16, v173, 2, s0
	ds_read_b128 v[12:15], v118 offset:18432
	ds_read_b128 v[20:23], v118 offset:18496
	ds_read_b128 v[8:11], v8 offset:7936
	v_lshl_add_u32 v17, v174, 2, s0
	ds_read_b32 v18, v16
	ds_read_b32 v32, v17
	ds_read_b128 v[24:27], v179 offset:27648
	ds_read_b128 v[28:31], v179 offset:27712
	s_waitcnt lgkmcnt(4)
	v_max_f32_e32 v8, v8, v8
	v_max_f32_e32 v16, v181, v181
	s_waitcnt lgkmcnt(1)
	v_mfma_f32_16x16x32_f16 v[24:27], v[12:15], v[24:27], 0
	v_max_f32_e32 v19, v16, v8
	v_max_f32_e32 v8, v9, v9
	v_max_f32_e32 v33, v16, v8
	v_max_f32_e32 v8, v10, v10
	v_max_f32_e32 v34, v16, v8
	v_max_f32_e32 v8, v11, v11
	v_sub_f32_e32 v17, v18, v19
	v_max_f32_e32 v35, v16, v8
	s_waitcnt lgkmcnt(0)
	v_mfma_f32_16x16x32_f16 v[8:11], v[20:23], v[28:31], v[24:27]
	v_mul_f32_e32 v17, 0x3fb8aa3b, v17
	v_exp_f32_e32 v17, v17
	v_sub_f32_e32 v19, v32, v19
	v_sub_f32_e32 v24, v18, v33
	v_mul_f32_e32 v24, 0x3fb8aa3b, v24
	v_exp_f32_e32 v24, v24
	v_cndmask_b32_e64 v36, v17, 0, s[26:27]
	s_nop 0
	v_fma_mixlo_f16 v17, v8, v36, 0
	ds_write_b16 v176, v17 offset:55296
	v_cndmask_b32_e64 v37, v24, 0, s[28:29]
	v_fma_mixlo_f16 v17, v9, v37, 0
	ds_write_b16 v176, v17 offset:55440
	v_sub_f32_e32 v17, v18, v34
	v_mul_f32_e32 v17, 0x3fb8aa3b, v17
	v_exp_f32_e32 v17, v17
	v_sub_f32_e32 v18, v18, v35
	v_mul_f32_e32 v18, 0x3fb8aa3b, v18
	v_exp_f32_e32 v24, v18
	v_cndmask_b32_e64 v18, v17, 0, s[24:25]
	v_fma_mixlo_f16 v17, v10, v18, 0
	ds_write_b16 v176, v17 offset:55584
	v_cndmask_b32_e64 v17, v24, 0, s[22:23]
	v_fma_mixlo_f16 v24, v11, v17, 0
	ds_write_b16 v176, v24 offset:55728
	ds_read_b128 v[24:27], v179 offset:29952
	ds_read_b128 v[28:31], v179 offset:30016
	s_waitcnt lgkmcnt(1)
	v_mfma_f32_16x16x32_f16 v[12:15], v[12:15], v[24:27], 0
	v_mul_f32_e32 v19, 0x3fb8aa3b, v19
	v_exp_f32_e32 v19, v19
	v_fma_f32 v8, v8, v36, 0
	s_waitcnt lgkmcnt(0)
	v_mfma_f32_16x16x32_f16 v[12:15], v[20:23], v[28:31], v[12:15]
	v_sub_f32_e32 v20, v32, v33
	v_mul_f32_e32 v20, 0x3fb8aa3b, v20
	v_exp_f32_e32 v20, v20
	v_cndmask_b32_e64 v19, v19, 0, s[20:21]
	v_mul_f32_e32 v9, v9, v37
	s_nop 2
	v_fmac_f32_e32 v8, v12, v19
	v_fma_mixlo_f16 v12, v12, v19, 0
	ds_write_b16 v176, v12 offset:55328
	v_cndmask_b32_e64 v12, v20, 0, s[18:19]
	v_mul_f32_e32 v19, v13, v12
	v_fma_mixlo_f16 v12, v13, v12, 0
	ds_write_b16 v176, v12 offset:55472
	v_sub_f32_e32 v12, v32, v34
	v_mul_f32_e32 v12, 0x3fb8aa3b, v12
	v_exp_f32_e32 v12, v12
	v_sub_f32_e32 v13, v32, v35
	v_mul_f32_e32 v13, 0x3fb8aa3b, v13
	v_exp_f32_e32 v20, v13
	v_cndmask_b32_e64 v13, v12, 0, s[16:17]
	v_fma_mixlo_f16 v12, v14, v13, 0
	ds_write_b16 v176, v12 offset:55616
	v_cndmask_b32_e64 v12, v20, 0, s[14:15]
	v_add_f32_dpp v8, v8, v8 quad_perm:[1,0,3,2] row_mask:0xf bank_mask:0xf bound_ctrl:1
	v_fma_mixlo_f16 v20, v15, v12, 0
	ds_write_b16 v176, v20 offset:55760
	v_add_f32_dpp v8, v8, v8 quad_perm:[2,3,0,1] row_mask:0xf bank_mask:0xf bound_ctrl:1
	s_nop 1
	v_add_f32_dpp v20, v8, v8 row_ror:4 row_mask:0xf bank_mask:0xf bound_ctrl:1
	v_add_u32_e32 v8, v170, v96
	s_nop 0
	v_mov_b32_dpp v21, v20 row_ror:8 row_mask:0xf bank_mask:0xf bound_ctrl:1
	s_and_saveexec_b64 s[0:1], s[12:13]
	v_add_f32_e32 v20, v20, v21
	ds_write_b32 v8, v20
	s_or_b64 exec, exec, s[0:1]
	v_add_f32_e32 v9, 0, v9
	v_add_f32_e32 v9, v9, v19
	v_mul_f32_e32 v10, v10, v18
	v_mul_f32_e32 v13, v14, v13
	v_add_f32_dpp v9, v9, v9 quad_perm:[1,0,3,2] row_mask:0xf bank_mask:0xf bound_ctrl:1
	s_nop 1
	v_add_f32_dpp v9, v9, v9 quad_perm:[2,3,0,1] row_mask:0xf bank_mask:0xf bound_ctrl:1
	s_nop 1
	v_add_f32_dpp v9, v9, v9 row_ror:4 row_mask:0xf bank_mask:0xf bound_ctrl:1
	s_nop 1
	v_mov_b32_dpp v14, v9 row_ror:8 row_mask:0xf bank_mask:0xf bound_ctrl:1
	s_and_saveexec_b64 s[0:1], s[12:13]
	v_add_f32_e32 v9, v9, v14
	ds_write_b32 v8, v9 offset:4
	s_or_b64 exec, exec, s[0:1]
	v_add_f32_e32 v10, 0, v10
	v_add_f32_e32 v10, v10, v13
	v_mul_f32_e32 v9, v11, v17
	v_mul_f32_e32 v11, v15, v12
	v_add_f32_dpp v10, v10, v10 quad_perm:[1,0,3,2] row_mask:0xf bank_mask:0xf bound_ctrl:1
	s_nop 1
	v_add_f32_dpp v10, v10, v10 quad_perm:[2,3,0,1] row_mask:0xf bank_mask:0xf bound_ctrl:1
	s_nop 1
	v_add_f32_dpp v10, v10, v10 row_ror:4 row_mask:0xf bank_mask:0xf bound_ctrl:1
	s_nop 1
	v_mov_b32_dpp v12, v10 row_ror:8 row_mask:0xf bank_mask:0xf bound_ctrl:1
	s_and_saveexec_b64 s[0:1], s[12:13]
	v_add_f32_e32 v10, v10, v12
	ds_write_b32 v8, v10 offset:8
	s_or_b64 exec, exec, s[0:1]
	v_add_f32_e32 v9, 0, v9
	v_add_f32_e32 v9, v9, v11
	s_nop 1
	v_add_f32_dpp v9, v9, v9 quad_perm:[1,0,3,2] row_mask:0xf bank_mask:0xf bound_ctrl:1
	s_nop 1
	v_add_f32_dpp v9, v9, v9 quad_perm:[2,3,0,1] row_mask:0xf bank_mask:0xf bound_ctrl:1
	s_nop 1
	v_add_f32_dpp v9, v9, v9 row_ror:4 row_mask:0xf bank_mask:0xf bound_ctrl:1
	s_nop 1
	v_mov_b32_dpp v10, v9 row_ror:8 row_mask:0xf bank_mask:0xf bound_ctrl:1
	s_and_saveexec_b64 s[0:1], s[12:13]
	v_add_f32_e32 v9, v9, v10
	ds_write_b32 v8, v9 offset:12
	s_or_b64 exec, exec, s[0:1]
	ds_read_b128 v[8:11], v158 offset:18432
	ds_read_b128 v[12:15], v169
	ds_read_b128 v[18:21], v169 offset:16
	s_waitcnt lgkmcnt(2)
	v_cvt_f32_f16_e32 v17, v10
	v_cvt_f32_f16_sdwa v10, v10 dst_sel:DWORD dst_unused:UNUSED_PAD src0_sel:WORD_1
	v_cvt_f32_f16_e32 v22, v11
	v_cvt_f32_f16_sdwa v11, v11 dst_sel:DWORD dst_unused:UNUSED_PAD src0_sel:WORD_1
	s_waitcnt lgkmcnt(0)
	v_mul_f32_e32 v17, v18, v17
	v_mul_f32_e32 v10, v19, v10
	v_fma_mix_f32 v12, v12, v8, v17 op_sel_hi:[0,1,0]
	v_fma_mix_f32 v8, v13, v8, v10 op_sel:[0,1,0] op_sel_hi:[0,1,0]
	v_add_f32_e32 v10, 0, v12
	v_add_f32_e32 v8, v8, v10
	v_mul_f32_e32 v10, v20, v22
	v_fma_mix_f32 v10, v14, v9, v10 op_sel_hi:[0,1,0]
	v_add_f32_e32 v8, v10, v8
	v_mul_f32_e32 v10, v21, v11
	v_fma_mix_f32 v9, v15, v9, v10 op_sel:[0,1,0] op_sel_hi:[0,1,0]
	v_add_f32_e32 v8, v9, v8
	s_nop 1
	v_add_f32_dpp v8, v8, v8 quad_perm:[1,0,3,2] row_mask:0xf bank_mask:0xf bound_ctrl:1
	s_nop 1
	v_add_f32_dpp v8, v8, v8 quad_perm:[2,3,0,1] row_mask:0xf bank_mask:0xf bound_ctrl:1
	s_nop 1
	v_mov_b32_dpp v9, v8 row_half_mirror row_mask:0xf bank_mask:0xf bound_ctrl:1
	s_and_saveexec_b64 s[0:1], s[10:11]
	s_cbranch_execz .LBB0_278
	s_waitcnt lgkmcnt(0)
	v_add_f32_e32 v8, v8, v9
	ds_write_b32 v168, v8
; #define LAS __attribute__((address_space(3)))
; __device__ __forceinline__ f32x4 mfma16(h16x8 a, h16x8 b, f32x4 c) { return __builtin_amdgcn_mfma_f32_16x16x32_f16(a, b, c, 0, 0, 0); }
; __device__ __forceinline__ float sigm(float x) { return __builtin_amdgcn_rcpf(1.f + __expf(-x)); }
; __device__ __forceinline__ void mlstm_chain(const Params& p, LAS unsigned char* lds, const MlChain ch) {
;     ...
;         {
;             const int tt = wave & 3, vp = wave >> 2, t = tt * 16 + fr;
;             h16x8 pa[2], qa[2];
; #pragma unroll
;             for (int ks = 0; ks < 2; ++ks) { pa[ks] = *(const LAS h16x8*)(PP + t * 72 + ks * 32 + fq * 8); qa[ks] = *(const LAS h16x8*)(QS + t * 72 + ks * 32 + fq * 8); }
;             const float mxt = fmaxf(mcur, CCM[c * 64 + t]);
;             const float sc = __expf(mcur - mxt);
;             const float den = DEN[t] + DEN[64 + t] + sc * DQN[t];
;             const float inv = __builtin_amdgcn_rcpf(fmaxf(fabsf(den), __expf(-(CBC[c * 64 + t] + mxt))));
;             float hv[2][4], ssq = 0.f;
; #pragma unroll
;             for (int j = 0; j < 2; ++j) {
;                 const int vt = vp * 2 + j;
;                 f32x4 a1 = {0.f, 0.f, 0.f, 0.f}, a2 = {0.f, 0.f, 0.f, 0.f};
; #pragma unroll
;                 for (int ks = 0; ks < 2; ++ks) {
;                     const h16x8 vb = *(const LAS h16x8*)(VT + (vt * 16 + fr) * 72 + ks * 32 + fq * 8);
;                     const h16x8 cbf = *(const LAS h16x8*)(CT + (vt * 16 + fr) * 72 + ks * 32 + fq * 8);
;                     a1 = mfma16(vb, pa[ks], a1); a2 = mfma16(cbf, qa[ks], a2);
;                 }
;                 const h16x4 o4 = j == 0 ? oc0 : oc1;
; #pragma unroll
;                 for (int r = 0; r < 4; ++r) { const float hh = (a1[r] + sc * a2[r]) * inv * sigm((float)o4[r]); hv[j][r] = hh; ssq += hh * hh; }
;             }
;             ssq += __shfl_xor(ssq, 16); ssq += __shfl_xor(ssq, 32);
;             if (fq == 0) SSQ[vp * 64 + t] = ssq;
.LBB0_278:
	s_or_b64 exec, exec, s[0:1]
	v_lshl_add_u32 v8, v163, 2, 0
	s_waitcnt lgkmcnt(0)
	s_barrier
	s_waitcnt lgkmcnt(0)
	v_add_u32_e32 v9, 0x18500, v8
	ds_read_b32 v9, v9
	ds_read_b128 v[10:13], v171 offset:55296
	v_add_u32_e32 v8, 0x14500, v8
	ds_read_b128 v[18:21], v171 offset:18496
	ds_read_b32 v8, v8
	s_waitcnt lgkmcnt(3)
	v_max_f32_e32 v9, v9, v9
	v_max_f32_e32 v9, v16, v9
	v_sub_f32_e32 v14, v181, v9
	v_mul_f32_e32 v14, 0x3fb8aa3b, v14
	v_exp_f32_e32 v46, v14
	ds_read_b32 v30, v165
	ds_read_b32 v31, v166
	ds_read_b32 v32, v167
	ds_read_b128 v[14:17], v164 offset:36864
	ds_read_b128 v[22:25], v171 offset:18432
	ds_read_b128 v[26:29], v171 offset:55360
	s_waitcnt lgkmcnt(4)
	v_add_f32_e32 v42, v30, v31
	v_add_f32_e32 v8, v9, v8
	s_waitcnt lgkmcnt(3)
	v_fmac_f32_e32 v42, v32, v46
	ds_read_b128 v[30:33], v164 offset:64512
	v_mul_f32_e32 v8, 0xbfb8aa3b, v8
	v_exp_f32_e32 v8, v8
	ds_read_b128 v[38:41], v164 offset:36928
	ds_read_b128 v[60:63], v164 offset:39168
	ds_read_b128 v[56:59], v164 offset:64576
	v_max_f32_e64 v8, |v42|, v8
	v_rcp_f32_e32 v64, v8
	s_waitcnt vmcnt(3)
	v_cvt_f32_f16_e32 v8, v104
	v_cvt_f32_f16_sdwa v9, v104 dst_sel:DWORD dst_unused:UNUSED_PAD src0_sel:WORD_1
	s_waitcnt lgkmcnt(6)
	v_mfma_f32_16x16x32_f16 v[14:17], v[14:17], v[10:13], 0
	ds_read_b128 v[42:45], v164 offset:39232
	v_mul_f32_e32 v8, 0xbfb8aa3b, v8
	v_mul_f32_e32 v9, 0xbfb8aa3b, v9
	s_waitcnt lgkmcnt(4)
	v_mfma_f32_16x16x32_f16 v[30:33], v[30:33], v[22:25], 0
	v_exp_f32_e32 v8, v8
	v_exp_f32_e32 v9, v9
	ds_read_b128 v[34:37], v147 offset:64
	s_waitcnt lgkmcnt(4)
	v_mfma_f32_16x16x32_f16 v[14:17], v[38:41], v[26:29], v[14:17]
	v_add_f32_e32 v8, 1.0, v8
	v_add_f32_e32 v9, 1.0, v9
	v_rcp_f32_e32 v8, v8
	s_waitcnt lgkmcnt(2)
	v_mfma_f32_16x16x32_f16 v[30:33], v[56:59], v[18:21], v[30:33]
	v_rcp_f32_e32 v9, v9
	ds_read_b128 v[38:41], v147
	v_mfma_f32_16x16x32_f16 v[56:59], v[60:63], v[10:13], 0
	s_nop 4
	v_fma_f32 v14, v46, v30, v14
	v_fma_f32 v15, v46, v31, v15
	v_cvt_f32_f16_e32 v30, v105
	v_cvt_f32_f16_sdwa v31, v105 dst_sel:DWORD dst_unused:UNUSED_PAD src0_sel:WORD_1
	v_pk_mul_f32 v[14:15], v[64:65], v[14:15] op_sel_hi:[0,1]
	v_pk_mul_f32 v[8:9], v[8:9], v[14:15]
	v_mul_f32_e32 v14, 0xbfb8aa3b, v30
	v_mul_f32_e32 v15, 0xbfb8aa3b, v31
	v_exp_f32_e32 v14, v14
	v_exp_f32_e32 v15, v15
	v_pk_fma_f32 v[10:11], v[46:47], v[32:33], v[16:17] op_sel_hi:[0,1,1]
	v_pk_mul_f32 v[10:11], v[64:65], v[10:11] op_sel_hi:[0,1]
	v_add_f32_e32 v14, 1.0, v14
	v_add_f32_e32 v15, 1.0, v15
	v_rcp_f32_e32 v14, v14
	v_rcp_f32_e32 v15, v15
	s_waitcnt vmcnt(2)
	v_cvt_f32_f16_e32 v32, v102
	v_cvt_f32_f16_sdwa v33, v102 dst_sel:DWORD dst_unused:UNUSED_PAD src0_sel:WORD_1
	v_pk_mul_f32 v[30:31], v[8:9], v[8:9]
	v_pk_mul_f32 v[12:13], v[14:15], v[10:11]
	s_waitcnt lgkmcnt(0)
	v_mfma_f32_16x16x32_f16 v[14:17], v[38:41], v[22:25], 0
	v_mul_f32_e64 v10, v12, v12
	v_mul_f32_e64 v11, v13, v13
	v_mfma_f32_16x16x32_f16 v[22:25], v[42:45], v[26:29], v[56:59]
	v_mul_f32_e32 v26, 0xbfb8aa3b, v32
	v_mul_f32_e32 v27, 0xbfb8aa3b, v33
	v_exp_f32_e32 v26, v26
	v_exp_f32_e32 v27, v27
	v_mfma_f32_16x16x32_f16 v[16:19], v[34:37], v[18:21], v[14:17]
	v_cvt_f32_f16_e32 v20, v103
	v_cvt_f32_f16_sdwa v21, v103 dst_sel:DWORD dst_unused:UNUSED_PAD src0_sel:WORD_1
	v_mul_f32_e32 v20, 0xbfb8aa3b, v20
	v_add_f32_e32 v14, 1.0, v26
	v_add_f32_e32 v15, 1.0, v27
	v_mul_f32_e32 v21, 0xbfb8aa3b, v21
	v_rcp_f32_e32 v14, v14
	v_rcp_f32_e32 v15, v15
	v_exp_f32_e32 v20, v20
	v_exp_f32_e32 v21, v21
	v_pk_fma_f32 v[16:17], v[46:47], v[16:17], v[22:23] op_sel_hi:[0,1,1]
	v_pk_mul_f32 v[16:17], v[64:65], v[16:17] op_sel_hi:[0,1]
	v_pk_mul_f32 v[16:17], v[14:15], v[16:17]
	v_add_f32_e32 v14, 1.0, v20
	v_add_f32_e32 v15, 1.0, v21
	v_rcp_f32_e32 v14, v14
	v_rcp_f32_e32 v15, v15
	v_add_f32_e32 v22, v30, v31
	v_pk_fma_f32 v[18:19], v[46:47], v[18:19], v[24:25] op_sel_hi:[0,1,1]
	v_add_f32_e32 v10, v10, v22
	v_pk_mul_f32 v[20:21], v[16:17], v[16:17]
	v_pk_mul_f32 v[18:19], v[64:65], v[18:19] op_sel_hi:[0,1]
	v_add_f32_e32 v10, v11, v10
	v_pk_mul_f32 v[14:15], v[14:15], v[18:19]
	v_add_f32_e32 v10, v10, v20
	v_pk_mul_f32 v[18:19], v[14:15], v[14:15]
	v_add_f32_e32 v10, v21, v10
	v_add_f32_e32 v10, v18, v10
	v_add_f32_e32 v10, v19, v10
	v_mov_b32_e32 v11, v10
	s_nop 1
	v_permlane16_swap_b32 v10, v11
	s_waitcnt lgkmcnt(0)
	v_add_f32_e32 v10, v10, v11
	v_mov_b32_e32 v11, v10
	s_nop 1
	v_permlane32_swap_b32 v10, v11
	s_and_saveexec_b64 s[0:1], vcc
	s_cbranch_execz .LBB0_280
	s_waitcnt lgkmcnt(0)
	v_add_f32_e32 v10, v10, v11
	v_add_u32_e32 v11, v160, v161
	ds_write_b32 v11, v10
; #define LAS __attribute__((address_space(3)))
; __device__ __forceinline__ f32x4 mfma16(h16x8 a, h16x8 b, f32x4 c) { return __builtin_amdgcn_mfma_f32_16x16x32_f16(a, b, c, 0, 0, 0); }
; __device__ __forceinline__ void lds_barrier() { asm volatile("s_waitcnt lgkmcnt(0)\n\ts_barrier" ::: "memory"); }
; __device__ __forceinline__ void mlstm_chain(const Params& p, LAS unsigned char* lds, const MlChain ch) {
;     ...
;             lds_barrier();
;             const float rstd = rsqrtf((SSQ[t] + SSQ[64 + t]) * (1.f / 64.f) + EPS);
;             if (t < nv) {
; #pragma unroll
;                 for (int j = 0; j < 2; ++j) {
;                     const int v0 = h * 64 + (vp * 2 + j) * 16 + fq * 4;
;                     const f32x4 nw = nwv[j];
;                     f32x4 o;
; #pragma unroll
;                     for (int r = 0; r < 4; ++r) o[r] = hv[j][r] * rstd * nw[r];
;                     *(h16x4*)(MIX + (size_t)(rowbase + t0 + t) * D + v0) = pack4(o);
;                 }
;             }
;         }
;         {
; #pragma unroll
;             for (int j = 0; j < 2; ++j) {
;                 const int vt = (wave >> 2) * 2 + j;
;                 Cacc[j] *= dec;
; #pragma unroll
;                 for (int ks = 0; ks < 2; ++ks) {
;                     const h16x8 kwf = *(const LAS h16x8*)(KW + (kt * 16 + fr) * 72 + ks * 32 + fq * 8);
;                     const h16x8 vf = *(const LAS h16x8*)(VT + (vt * 16 + fr) * 72 + ks * 32 + fq * 8);
;                     Cacc[j] = mfma16(kwf, vf, Cacc[j]);
;                 }
;                 *(LAS h16x4*)(CT + (vt * 16 + fr) * 72 + kt * 16 + fq * 4) = pack4(Cacc[j]);
;             }
;             {
;                 const int kch = tid >> 3, part = tid & 7;
;                 const h16x8 x = *(const LAS h16x8*)(KW + kch * 72 + part * 8);
;                 float a = 0.f;
; #pragma unroll
;                 for (int j = 0; j < 8; ++j) a += (float)x[j];
;                 a = dpp_add<0xB1>(a); a = dpp_add<0x4E>(a); a += __shfl_xor(a, 4);
;                 if (part == 0) NL[kch] = dec * NL[kch] + a;
.LBB0_280:
	s_or_b64 exec, exec, s[0:1]
	s_waitcnt lgkmcnt(0)
	s_barrier
	ds_read_b32 v10, v160
	s_waitcnt lgkmcnt(1)
	ds_read_b32 v11, v162
	ds_read_b128 v[20:23], v159 offset:46080
	v_mov_b32_e32 v18, 0x358637bd
	s_mov_b32 s0, 0x800000
	ds_read_b128 v[24:27], v99 offset:36864
	ds_read_b128 v[28:31], v159 offset:46144
	s_waitcnt lgkmcnt(3)
	v_add_f32_e32 v10, v10, v11
	v_fmac_f32_e32 v18, 0x3c800000, v10
	v_sub_f32_e32 v11, v111, v110
	v_mul_f32_e32 v10, 0x4b800000, v18
	v_cmp_gt_f32_e32 vcc, s0, v18
	v_mul_f32_e32 v11, 0x3fb8aa3b, v11
	ds_read_b128 v[36:39], v99 offset:36928
	v_cndmask_b32_e32 v10, v18, v10, vcc
	v_exp_f32_e32 v18, v11
	v_rsq_f32_e32 v10, v10
	v_pk_mul_f32 v[34:35], v[54:55], v[18:19] op_sel_hi:[1,0]
	v_pk_mul_f32 v[32:33], v[52:53], v[18:19] op_sel_hi:[1,0]
	v_mul_f32_e32 v11, 0x45800000, v10
	v_cndmask_b32_e32 v40, v10, v11, vcc
	s_waitcnt lgkmcnt(2)
	v_mfma_f32_16x16x32_f16 v[24:27], v[20:23], v[24:27], v[32:35]
	v_or_b32_e32 v10, 0x7c0, v143
	v_ashrrev_i32_e32 v11, 31, v10
	v_pk_mul_f32 v[8:9], v[8:9], v[40:41] op_sel_hi:[1,0]
	v_lshlrev_b64 v[42:43], 11, v[10:11]
	v_pk_mul_f32 v[4:5], v[4:5], v[8:9]
	s_waitcnt lgkmcnt(0)
	v_mfma_f32_16x16x32_f16 v[8:11], v[28:31], v[36:39], v[24:27]
	v_cvt_pk_f16_f32 v44, v4, v5
	v_pk_mul_f32 v[34:35], v[50:51], v[18:19] op_sel_hi:[1,0]
	v_pk_mul_f32 v[32:33], v[48:49], v[18:19] op_sel_hi:[1,0]
	v_pk_mul_f32 v[16:17], v[16:17], v[40:41] op_sel_hi:[1,0]
	v_pk_mul_f32 v[14:15], v[14:15], v[40:41] op_sel_hi:[1,0]
	s_nop 2
	v_cvt_pk_f16_f32 v5, v10, v11
	v_cvt_pk_f16_f32 v4, v8, v9
	ds_write_b64 v113, v[4:5] offset:64512
	ds_read_b128 v[24:27], v112 offset:36864
	ds_read_b128 v[36:39], v112 offset:36928
	s_waitcnt lgkmcnt(1)
	v_mfma_f32_16x16x32_f16 v[20:23], v[20:23], v[24:27], v[32:35]
	v_mul_f32_e64 v4, v12, v40
	v_mul_f32_e64 v5, v13, v40
	v_pk_mul_f32 v[0:1], v[0:1], v[16:17]
	v_pk_mul_f32 v[4:5], v[6:7], v[4:5]
	v_cvt_pk_f16_f32 v16, v0, v1
	v_cvt_pk_f16_f32 v45, v4, v5
	s_waitcnt lgkmcnt(0)
	v_mfma_f32_16x16x32_f16 v[4:7], v[28:31], v[36:39], v[20:23]
	v_mul_f32_e64 v2, v2, v14
	v_mul_f32_e64 v3, v3, v15
	v_lshl_add_u64 v[12:13], v[100:101], 0, v[42:43]
	global_store_dwordx2 v[12:13], v[44:45], off
	s_nop 3
	v_cvt_pk_f16_f32 v21, v6, v7
	v_cvt_pk_f16_f32 v20, v4, v5
	ds_write_b64 v114, v[20:21] offset:64512
	ds_read_b128 v[20:23], v158 offset:46080
	s_waitcnt lgkmcnt(0)
	v_cvt_f32_f16_e32 v0, v20
	v_cvt_f32_f16_sdwa v1, v20 dst_sel:DWORD dst_unused:UNUSED_PAD src0_sel:WORD_1
	v_cvt_f32_f16_e32 v17, v21
	v_cvt_f32_f16_sdwa v19, v21 dst_sel:DWORD dst_unused:UNUSED_PAD src0_sel:WORD_1
	v_add_f32_e32 v0, 0, v0
	v_add_f32_e32 v0, v0, v1
	v_cvt_f32_f16_e32 v1, v22
	v_add_f32_e32 v0, v0, v17
	v_cvt_f32_f16_sdwa v17, v22 dst_sel:DWORD dst_unused:UNUSED_PAD src0_sel:WORD_1
	v_add_f32_e32 v0, v0, v19
	v_cvt_f32_f16_e32 v19, v23
	v_cvt_f32_f16_sdwa v20, v23 dst_sel:DWORD dst_unused:UNUSED_PAD src0_sel:WORD_1
	v_add_f32_e32 v0, v0, v1
	v_add_f32_e32 v0, v0, v17
	v_add_f32_e32 v0, v0, v19
	v_add_f32_e32 v0, v0, v20
	v_cvt_pk_f16_f32 v17, v2, v3
	global_store_dwordx2 v[12:13], v[16:17], off offset:32
	v_add_f32_dpp v0, v0, v0 quad_perm:[1,0,3,2] row_mask:0xf bank_mask:0xf bound_ctrl:1
	s_nop 1
	v_add_f32_dpp v0, v0, v0 quad_perm:[2,3,0,1] row_mask:0xf bank_mask:0xf bound_ctrl:1
	s_nop 1
	v_mov_b32_dpp v1, v0 row_half_mirror row_mask:0xf bank_mask:0xf bound_ctrl:1
	s_and_saveexec_b64 s[0:1], s[10:11]
	s_cbranch_execz .LBB0_282
	ds_read_b32 v2, v145
	s_waitcnt lgkmcnt(1)
	v_add_f32_e32 v0, v0, v1
	s_waitcnt lgkmcnt(0)
	v_fmac_f32_e32 v0, v18, v2
	ds_write_b32 v145, v0

; #define PG8_STAGE(bufoff, gbase, voff) do { _Pragma("unroll") for (int _i = 0; _i < 2; ++_i) \
;         __builtin_amdgcn_global_load_lds((const unsigned*)((const char*)(gbase) + (voff)[_i]), (LAS unsigned*)(lds + (bufoff) + ldsw + _i * 8192), 16, 0, 0); } while (0)
; #define PG8_LDA(dst, b, h) do { _Pragma("unroll") for (int m = 0; m < 4; ++m) _Pragma("unroll") for (int k = 0; k < 2; ++k) dst[m][k] = *(const LAS h16x8*)(lds + PG8_SA(b, h) + aoff + m * 2048 + k * 1024); } while (0)
; #define PG8_LDB(dst, b, h) do { _Pragma("unroll") for (int n = 0; n < 2; ++n) _Pragma("unroll") for (int k = 0; k < 2; ++k) dst[n][k] = *(const LAS h16x8*)(lds + PG8_SB(b, h) + boff + n * 2048 + k * 1024); } while (0)
; #define PG8_MMA(ai, bj, At, Bt) do { __builtin_amdgcn_s_setprio(1); _Pragma("unroll") for (int m = 0; m < 4; ++m) _Pragma("unroll") for (int n = 0; n < 2; ++n) _Pragma("unroll") for (int k = 0; k < 2; ++k) \
;         acc[ai][bj][m][n] = __builtin_amdgcn_mfma_f32_16x16x32_f16(Bt[n][k], At[m][k], acc[ai][bj][m][n], 0, 0, 0); __builtin_amdgcn_s_setprio(0); } while (0)
; #define PG8_WAIT_V(n) asm volatile("s_waitcnt vmcnt(" #n ")" ::: "memory")
; #define PG8_WAIT_L(n) asm volatile("s_waitcnt lgkmcnt(" #n ")" ::: "memory")
; #define PG8_BAR __builtin_amdgcn_s_barrier()
; #define PG8_SCHED __builtin_amdgcn_sched_barrier(0)
; template <class Epi>
; __device__ __forceinline__ void gemm_phase(LAS unsigned char* lds, const Gemm g, const StaticOrder& S, const Epi& E) {
;     ...
;             PG8_LDB(B0, 0, 0); PG8_SCHED; PG8_LDA(At, 0, 0); PG8_STAGE(PG8_SA(1, 1), a1 + hstep, voffA);
;             PG8_WAIT_L(8); PG8_BAR; PG8_WAIT_L(0); PG8_MMA(0, 0, At, B0); PG8_BAR; PG8_SCHED;
;             PG8_LDB(B1, 0, 1); PG8_STAGE(PG8_SB(0, 0), b2, voffB);
;             PG8_BAR; PG8_WAIT_L(0); PG8_MMA(0, 1, At, B1); PG8_BAR;
;             PG8_LDA(At, 0, 1); PG8_STAGE(PG8_SA(0, 0), a2, voffA);
;             PG8_BAR; PG8_WAIT_L(0); PG8_MMA(1, 0, At, B0); PG8_BAR; PG8_SCHED;
;             PG8_STAGE(PG8_SB(0, 1), b2 + hstep, voffB);
;             PG8_WAIT_V(6); PG8_BAR; PG8_MMA(1, 1, At, B1); PG8_BAR;
.LBB0_422:
	ds_read_b128 v[162:165], v145
	ds_read_b128 v[168:171], v145 offset:1024
	ds_read_b128 v[172:175], v145 offset:2048
	ds_read_b128 v[176:179], v145 offset:3072
	s_add_u32 s28, s26, 0xfffc0080
	s_addc_u32 s29, s27, -1
	s_cmp_eq_u32 s50, 12
	s_cselect_b32 s31, s17, s29
	s_cselect_b32 s30, s23, s28
	s_cselect_b32 s29, s13, s49
	s_cselect_b32 s28, s47, s48
	v_lshl_add_u64 v[212:213], s[26:27], 0, v[154:155]
	s_add_i32 m0, s25, 0xc000
	ds_read_b128 v[180:183], v147
	ds_read_b128 v[184:187], v147 offset:1024
	ds_read_b128 v[188:191], v147 offset:2048
	ds_read_b128 v[192:195], v147 offset:3072
	ds_read_b128 v[196:199], v147 offset:4096
	ds_read_b128 v[200:203], v147 offset:5120
	ds_read_b128 v[204:207], v147 offset:6144
	ds_read_b128 v[208:211], v147 offset:7168
	global_load_lds_dwordx4 v[212:213], off
	v_lshl_add_u64 v[212:213], s[26:27], 0, v[156:157]
	s_add_i32 m0, s25, 0xe000
	s_nop 0
	global_load_lds_dwordx4 v[212:213], off
	s_waitcnt lgkmcnt(8)
	s_barrier
	s_waitcnt lgkmcnt(0)
	s_setprio 1
	s_waitcnt lgkmcnt(0)
	v_mfma_f32_16x16x32_f16 v[124:127], v[162:165], v[180:183], v[124:127]
	v_mfma_f32_16x16x32_f16 v[120:123], v[172:175], v[180:183], v[120:123]
	v_mfma_f32_16x16x32_f16 v[108:111], v[162:165], v[188:191], v[108:111]
	v_mfma_f32_16x16x32_f16 v[104:107], v[172:175], v[188:191], v[104:107]
	v_mfma_f32_16x16x32_f16 v[92:95], v[162:165], v[196:199], v[92:95]
	v_mfma_f32_16x16x32_f16 v[88:91], v[172:175], v[196:199], v[88:91]
	v_mfma_f32_16x16x32_f16 v[76:79], v[162:165], v[204:207], v[76:79]
	v_mfma_f32_16x16x32_f16 v[72:75], v[172:175], v[204:207], v[72:75]
	v_mfma_f32_16x16x32_f16 v[124:127], v[168:171], v[184:187], v[124:127]
	v_mfma_f32_16x16x32_f16 v[120:123], v[176:179], v[184:187], v[120:123]
	v_mfma_f32_16x16x32_f16 v[108:111], v[168:171], v[192:195], v[108:111]
	v_mfma_f32_16x16x32_f16 v[104:107], v[176:179], v[192:195], v[104:107]
	v_mfma_f32_16x16x32_f16 v[92:95], v[168:171], v[200:203], v[92:95]
	v_mfma_f32_16x16x32_f16 v[88:91], v[176:179], v[200:203], v[88:91]
	v_mfma_f32_16x16x32_f16 v[76:79], v[168:171], v[208:211], v[76:79]
	v_mfma_f32_16x16x32_f16 v[72:75], v[176:179], v[208:211], v[72:75]
	s_setprio 0
	s_barrier
	s_add_i32 s51, s45, s37
	v_lshl_add_u64 v[228:229], s[28:29], 0, v[148:149]
	s_mov_b32 m0, s51
	ds_read_b128 v[212:215], v166
	ds_read_b128 v[216:219], v166 offset:1024
	ds_read_b128 v[220:223], v166 offset:2048
	ds_read_b128 v[224:227], v166 offset:3072
	global_load_lds_dwordx4 v[228:229], off
	v_lshl_add_u64 v[230:231], s[28:29], 0, v[152:153]
	s_add_i32 m0, s51, 0x2000
	s_nop 0
	global_load_lds_dwordx4 v[230:231], off
	s_barrier
	s_waitcnt lgkmcnt(0)
	s_setprio 1
	s_waitcnt lgkmcnt(0)
	v_mfma_f32_16x16x32_f16 v[116:119], v[212:215], v[180:183], v[116:119]
	v_mfma_f32_16x16x32_f16 v[112:115], v[220:223], v[180:183], v[112:115]
	v_mfma_f32_16x16x32_f16 v[100:103], v[212:215], v[188:191], v[100:103]
	v_mfma_f32_16x16x32_f16 v[96:99], v[220:223], v[188:191], v[96:99]
	v_mfma_f32_16x16x32_f16 v[84:87], v[212:215], v[196:199], v[84:87]
	v_mfma_f32_16x16x32_f16 v[80:83], v[220:223], v[196:199], v[80:83]
	v_mfma_f32_16x16x32_f16 v[68:71], v[212:215], v[204:207], v[68:71]
	v_mfma_f32_16x16x32_f16 v[64:67], v[220:223], v[204:207], v[64:67]
	v_mfma_f32_16x16x32_f16 v[116:119], v[216:219], v[184:187], v[116:119]
	v_mfma_f32_16x16x32_f16 v[112:115], v[224:227], v[184:187], v[112:115]
	v_mfma_f32_16x16x32_f16 v[100:103], v[216:219], v[192:195], v[100:103]
	v_mfma_f32_16x16x32_f16 v[96:99], v[224:227], v[192:195], v[96:99]
	v_mfma_f32_16x16x32_f16 v[84:87], v[216:219], v[200:203], v[84:87]
	v_mfma_f32_16x16x32_f16 v[80:83], v[224:227], v[200:203], v[80:83]
	v_mfma_f32_16x16x32_f16 v[68:71], v[216:219], v[208:211], v[68:71]
	v_mfma_f32_16x16x32_f16 v[64:67], v[224:227], v[208:211], v[64:67]
	s_setprio 0
	s_mov_b32 m0, s25
	v_lshl_add_u64 v[232:233], s[30:31], 0, v[142:143]
	s_barrier
	ds_read_b128 v[180:183], v147 offset:16384
	ds_read_b128 v[184:187], v147 offset:17408
	ds_read_b128 v[188:191], v147 offset:18432
	ds_read_b128 v[192:195], v147 offset:19456
	ds_read_b128 v[196:199], v147 offset:20480
	ds_read_b128 v[200:203], v147 offset:21504
	ds_read_b128 v[204:207], v147 offset:22528
	ds_read_b128 v[208:211], v147 offset:23552
	global_load_lds_dwordx4 v[232:233], off
	v_lshl_add_u64 v[234:235], s[30:31], 0, v[150:151]
	s_mov_b32 m0, s38
	s_nop 0
	global_load_lds_dwordx4 v[234:235], off
	s_barrier
	s_waitcnt lgkmcnt(0)
	s_setprio 1
	s_waitcnt lgkmcnt(0)
	v_mfma_f32_16x16x32_f16 v[60:63], v[162:165], v[180:183], v[60:63]
	v_mfma_f32_16x16x32_f16 v[56:59], v[172:175], v[180:183], v[56:59]
	v_mfma_f32_16x16x32_f16 v[44:47], v[162:165], v[188:191], v[44:47]
	v_mfma_f32_16x16x32_f16 v[40:43], v[172:175], v[188:191], v[40:43]
	v_mfma_f32_16x16x32_f16 v[28:31], v[162:165], v[196:199], v[28:31]
	v_mfma_f32_16x16x32_f16 v[24:27], v[172:175], v[196:199], v[24:27]
	v_mfma_f32_16x16x32_f16 v[12:15], v[162:165], v[204:207], v[12:15]
	v_mfma_f32_16x16x32_f16 v[8:11], v[172:175], v[204:207], v[8:11]
	v_mfma_f32_16x16x32_f16 v[60:63], v[168:171], v[184:187], v[60:63]
	v_mfma_f32_16x16x32_f16 v[56:59], v[176:179], v[184:187], v[56:59]
	v_mfma_f32_16x16x32_f16 v[44:47], v[168:171], v[192:195], v[44:47]
	v_mfma_f32_16x16x32_f16 v[40:43], v[176:179], v[192:195], v[40:43]
	v_mfma_f32_16x16x32_f16 v[28:31], v[168:171], v[200:203], v[28:31]
	v_mfma_f32_16x16x32_f16 v[24:27], v[176:179], v[200:203], v[24:27]
	v_mfma_f32_16x16x32_f16 v[12:15], v[168:171], v[208:211], v[12:15]
	v_mfma_f32_16x16x32_f16 v[8:11], v[176:179], v[208:211], v[8:11]
	s_setprio 0
	s_barrier
; #define PG8_STAGE(bufoff, gbase, voff) do { _Pragma("unroll") for (int _i = 0; _i < 2; ++_i) \
;         __builtin_amdgcn_global_load_lds((const unsigned*)((const char*)(gbase) + (voff)[_i]), (LAS unsigned*)(lds + (bufoff) + ldsw + _i * 8192), 16, 0, 0); } while (0)
; #define PG8_LDA(dst, b, h) do { _Pragma("unroll") for (int m = 0; m < 4; ++m) _Pragma("unroll") for (int k = 0; k < 2; ++k) dst[m][k] = *(const LAS h16x8*)(lds + PG8_SA(b, h) + aoff + m * 2048 + k * 1024); } while (0)
; #define PG8_LDB(dst, b, h) do { _Pragma("unroll") for (int n = 0; n < 2; ++n) _Pragma("unroll") for (int k = 0; k < 2; ++k) dst[n][k] = *(const LAS h16x8*)(lds + PG8_SB(b, h) + boff + n * 2048 + k * 1024); } while (0)
; #define PG8_MMA(ai, bj, At, Bt) do { __builtin_amdgcn_s_setprio(1); _Pragma("unroll") for (int m = 0; m < 4; ++m) _Pragma("unroll") for (int n = 0; n < 2; ++n) _Pragma("unroll") for (int k = 0; k < 2; ++k) \
;         acc[ai][bj][m][n] = __builtin_amdgcn_mfma_f32_16x16x32_f16(Bt[n][k], At[m][k], acc[ai][bj][m][n], 0, 0, 0); __builtin_amdgcn_s_setprio(0); } while (0)
; #define PG8_WAIT_V(n) asm volatile("s_waitcnt vmcnt(" #n ")" ::: "memory")
; #define PG8_WAIT_L(n) asm volatile("s_waitcnt lgkmcnt(" #n ")" ::: "memory")
; #define PG8_BAR __builtin_amdgcn_s_barrier()
; #define PG8_SCHED __builtin_amdgcn_sched_barrier(0)
; template <class Epi>
; __device__ __forceinline__ void gemm_phase(LAS unsigned char* lds, const Gemm g, const StaticOrder& S, const Epi& E) {
;     ...
;             PG8_WAIT_V(6); PG8_BAR; PG8_MMA(1, 1, At, B1); PG8_BAR;
;             PG8_LDB(B0, 1, 0); PG8_SCHED; PG8_LDA(At, 1, 0); PG8_STAGE(PG8_SA(0, 1), a2 + hstep, voffA);
;             PG8_WAIT_L(8); PG8_BAR; PG8_WAIT_L(0); PG8_MMA(0, 0, At, B0); PG8_BAR; PG8_SCHED;
;             PG8_LDB(B1, 1, 1); PG8_STAGE(PG8_SB(1, 0), b3, voffB);
;             PG8_BAR; PG8_WAIT_L(0); PG8_MMA(0, 1, At, B1); PG8_BAR;
;             PG8_LDA(At, 1, 1); PG8_STAGE(PG8_SA(1, 0), a3, voffA);
;             PG8_BAR; PG8_WAIT_L(0); PG8_MMA(1, 0, At, B0); PG8_BAR; PG8_SCHED;
	s_add_u32 s52, s28, 0x40000
	s_addc_u32 s53, s29, 0
	s_add_i32 s51, s46, s37
	v_lshl_add_u64 v[162:163], s[52:53], 0, v[148:149]
	s_mov_b32 m0, s51
	s_nop 0
	global_load_lds_dwordx4 v[162:163], off
	v_lshl_add_u64 v[162:163], s[52:53], 0, v[152:153]
	s_add_i32 m0, s51, 0x2000
	s_nop 0
	global_load_lds_dwordx4 v[162:163], off
	s_waitcnt vmcnt(6)
	s_barrier
	s_setprio 1
	v_mfma_f32_16x16x32_f16 v[52:55], v[212:215], v[180:183], v[52:55]
	v_mfma_f32_16x16x32_f16 v[48:51], v[220:223], v[180:183], v[48:51]
	v_mfma_f32_16x16x32_f16 v[36:39], v[212:215], v[188:191], v[36:39]
	v_mfma_f32_16x16x32_f16 v[32:35], v[220:223], v[188:191], v[32:35]
	v_mfma_f32_16x16x32_f16 v[20:23], v[212:215], v[196:199], v[20:23]
	v_mfma_f32_16x16x32_f16 v[16:19], v[220:223], v[196:199], v[16:19]
	v_mfma_f32_16x16x32_f16 v[4:7], v[212:215], v[204:207], v[4:7]
	v_mfma_f32_16x16x32_f16 v[0:3], v[220:223], v[204:207], v[0:3]
	v_mfma_f32_16x16x32_f16 v[52:55], v[216:219], v[184:187], v[52:55]
	v_mfma_f32_16x16x32_f16 v[48:51], v[224:227], v[184:187], v[48:51]
	v_mfma_f32_16x16x32_f16 v[36:39], v[216:219], v[192:195], v[36:39]
	v_mfma_f32_16x16x32_f16 v[32:35], v[224:227], v[192:195], v[32:35]
	v_mfma_f32_16x16x32_f16 v[20:23], v[216:219], v[200:203], v[20:23]
	v_mfma_f32_16x16x32_f16 v[16:19], v[224:227], v[200:203], v[16:19]
	v_mfma_f32_16x16x32_f16 v[4:7], v[216:219], v[208:211], v[4:7]
	v_mfma_f32_16x16x32_f16 v[0:3], v[224:227], v[208:211], v[0:3]
	s_setprio 0
	s_add_i32 s51, 0, 0x18000
	v_add_u32_e32 v167, s51, v139
	s_barrier
	ds_read_b128 v[162:165], v167
	ds_read_b128 v[168:171], v167 offset:1024
	ds_read_b128 v[172:175], v167 offset:2048
	ds_read_b128 v[176:179], v167 offset:3072
	s_add_u32 s30, s30, 0x40000
	s_addc_u32 s31, s31, 0
	s_mov_b32 m0, s39
	v_lshl_add_u64 v[212:213], s[30:31], 0, v[142:143]
	ds_read_b128 v[180:183], v147 offset:32768
	ds_read_b128 v[184:187], v147 offset:33792
	ds_read_b128 v[188:191], v147 offset:34816
	ds_read_b128 v[192:195], v147 offset:35840
	ds_read_b128 v[196:199], v147 offset:36864
	ds_read_b128 v[200:203], v147 offset:37888
	ds_read_b128 v[204:207], v147 offset:38912
	ds_read_b128 v[208:211], v147 offset:39936
	global_load_lds_dwordx4 v[212:213], off
	v_lshl_add_u64 v[212:213], s[30:31], 0, v[150:151]
	s_mov_b32 m0, s41
	s_nop 0
	global_load_lds_dwordx4 v[212:213], off
	s_waitcnt lgkmcnt(8)
	s_barrier
	s_waitcnt lgkmcnt(0)
	s_setprio 1
	s_waitcnt lgkmcnt(0)
	v_mfma_f32_16x16x32_f16 v[124:127], v[162:165], v[180:183], v[124:127]
	v_mfma_f32_16x16x32_f16 v[120:123], v[172:175], v[180:183], v[120:123]
	v_mfma_f32_16x16x32_f16 v[108:111], v[162:165], v[188:191], v[108:111]
	v_mfma_f32_16x16x32_f16 v[104:107], v[172:175], v[188:191], v[104:107]
	v_mfma_f32_16x16x32_f16 v[92:95], v[162:165], v[196:199], v[92:95]
	v_mfma_f32_16x16x32_f16 v[88:91], v[172:175], v[196:199], v[88:91]
	v_mfma_f32_16x16x32_f16 v[76:79], v[162:165], v[204:207], v[76:79]
	v_mfma_f32_16x16x32_f16 v[72:75], v[172:175], v[204:207], v[72:75]
	v_mfma_f32_16x16x32_f16 v[124:127], v[168:171], v[184:187], v[124:127]
	v_mfma_f32_16x16x32_f16 v[120:123], v[176:179], v[184:187], v[120:123]
	v_mfma_f32_16x16x32_f16 v[108:111], v[168:171], v[192:195], v[108:111]
	v_mfma_f32_16x16x32_f16 v[104:107], v[176:179], v[192:195], v[104:107]
	v_mfma_f32_16x16x32_f16 v[92:95], v[168:171], v[200:203], v[92:95]
	v_mfma_f32_16x16x32_f16 v[88:91], v[176:179], v[200:203], v[88:91]
	v_mfma_f32_16x16x32_f16 v[76:79], v[168:171], v[208:211], v[76:79]
	v_mfma_f32_16x16x32_f16 v[72:75], v[176:179], v[208:211], v[72:75]
	s_setprio 0
	s_barrier
	s_add_i32 s30, 0, 0x1c000
	s_add_i32 s31, s51, s37
	v_add_u32_e32 v167, s30, v139
	v_lshl_add_u64 v[228:229], v[228:229], 0, s[0:1]
	s_mov_b32 m0, s31
	ds_read_b128 v[212:215], v167
	ds_read_b128 v[216:219], v167 offset:1024
	ds_read_b128 v[220:223], v167 offset:2048
	ds_read_b128 v[224:227], v167 offset:3072
	global_load_lds_dwordx4 v[228:229], off
	v_lshl_add_u64 v[228:229], v[230:231], 0, s[0:1]
	s_add_i32 m0, s31, 0x2000
	s_nop 0
	global_load_lds_dwordx4 v[228:229], off
	s_barrier
	s_waitcnt lgkmcnt(0)
	s_setprio 1
	s_waitcnt lgkmcnt(0)
	v_mfma_f32_16x16x32_f16 v[116:119], v[212:215], v[180:183], v[116:119]
	v_mfma_f32_16x16x32_f16 v[112:115], v[220:223], v[180:183], v[112:115]
	v_mfma_f32_16x16x32_f16 v[100:103], v[212:215], v[188:191], v[100:103]
	v_mfma_f32_16x16x32_f16 v[96:99], v[220:223], v[188:191], v[96:99]
	v_mfma_f32_16x16x32_f16 v[84:87], v[212:215], v[196:199], v[84:87]
	v_mfma_f32_16x16x32_f16 v[80:83], v[220:223], v[196:199], v[80:83]
	v_mfma_f32_16x16x32_f16 v[68:71], v[212:215], v[204:207], v[68:71]
	v_mfma_f32_16x16x32_f16 v[64:67], v[220:223], v[204:207], v[64:67]
	v_mfma_f32_16x16x32_f16 v[116:119], v[216:219], v[184:187], v[116:119]
	v_mfma_f32_16x16x32_f16 v[112:115], v[224:227], v[184:187], v[112:115]
	v_mfma_f32_16x16x32_f16 v[100:103], v[216:219], v[192:195], v[100:103]
	v_mfma_f32_16x16x32_f16 v[96:99], v[224:227], v[192:195], v[96:99]
	v_mfma_f32_16x16x32_f16 v[84:87], v[216:219], v[200:203], v[84:87]
	v_mfma_f32_16x16x32_f16 v[80:83], v[224:227], v[200:203], v[80:83]
	v_mfma_f32_16x16x32_f16 v[68:71], v[216:219], v[208:211], v[68:71]
	v_mfma_f32_16x16x32_f16 v[64:67], v[224:227], v[208:211], v[64:67]
	s_setprio 0
	s_mov_b32 m0, s43
	v_lshl_add_u64 v[228:229], v[232:233], 0, s[0:1]
	s_barrier
	ds_read_b128 v[180:183], v147 offset:49152
	ds_read_b128 v[184:187], v147 offset:50176
	ds_read_b128 v[188:191], v147 offset:51200
	ds_read_b128 v[192:195], v147 offset:52224
	ds_read_b128 v[196:199], v147 offset:53248
	ds_read_b128 v[200:203], v147 offset:54272
	ds_read_b128 v[204:207], v147 offset:55296
	ds_read_b128 v[208:211], v147 offset:56320
	global_load_lds_dwordx4 v[228:229], off
	v_lshl_add_u64 v[228:229], v[234:235], 0, s[0:1]
	s_mov_b32 m0, s44
	s_nop 0
	global_load_lds_dwordx4 v[228:229], off
	s_barrier
; template <class Epi>
; __device__ __forceinline__ void gemm_phase(LAS unsigned char* lds, const Gemm g, const StaticOrder& S, const Epi& E) {
;     ...
;             PG8_BAR; PG8_WAIT_L(0); PG8_MMA(1, 0, At, B0); PG8_BAR; PG8_SCHED;
;             PG8_STAGE(PG8_SB(1, 1), b3 + hstep, voffB);
;             PG8_WAIT_V(6); PG8_BAR; PG8_MMA(1, 1, At, B1); PG8_BAR;
;         }
;     __device__ __forceinline__ void operator()(const f32x4 (&acc)[2][2][4][2], const pg8::Unit& u, int wr, int wc, int fr, int fq) const {
;         const int row0 = u.pm * 256 + wr * 64 + fr, col0 = u.pn * 256 + wc * 32 + 8 * fq;
; #pragma unroll
;         for (int ai = 0; ai < 2; ++ai)
; #pragma unroll
;             for (int m = 0; m < 4; ++m) {
;                 const int row = row0 + ai * 128 + m * 16;
;                 float ss = 0.f, rstd = 1.f;
;                 if (MODE == 2) rstd = rsqrtf(rowss[row] * (1.f / 1024.f) + EPS);
; #pragma unroll
;                 for (int bj = 0; bj < 2; ++bj) {
;                     const int c = col0 + bj * 128;
;                     f32x4 v0 = acc[ai][bj][m][0], v1 = acc[ai][bj][m][1];
;                     if (MODE == 1) {
;                         const float* rp = res + (size_t)row * ldres + c;
;                         v0 += *(const f32x4*)rp; v1 += *(const f32x4*)(rp + 4);
;                     }
;                     if (MODE == 3) {
;                         const h16x8 r8 = *(const h16x8*)(res16 + (size_t)row * ldres + c);
; #pragma unroll
;                         for (int j = 0; j < 4; ++j) { v0[j] += (float)r8[j]; v1[j] += (float)r8[4 + j]; }
;                     }
;                     if (MODE == 1 || MODE == 3) {
;                         ss += v0[0] * v0[0] + v0[1] * v0[1] + v0[2] * v0[2] + v0[3] * v0[3] + v1[0] * v1[0] + v1[1] * v1[1] + v1[2] * v1[2] + v1[3] * v1[3];
;                     }
;                     if (MODE == 2) {
; #pragma unroll
;                         for (int j = 0; j < 4; ++j) { float a = fmaxf(v0[j] * rstd, 0.f), b = fmaxf(v1[j] * rstd, 0.f); v0[j] = a * a; v1[j] = b * b; }
;                     }
;                     *(h16x8*)(o16 + (size_t)row * ld16 + c) = pack8(v0, v1);
;                 }
;                 if (MODE == 1 || MODE == 3) {
;                     ss += __shfl_xor(ss, 16); ss += __shfl_xor(ss, 32);
;                     if (fq == 0) atomicAdd(rowss + row, ss);
	s_waitcnt lgkmcnt(0)
	s_setprio 1
	s_waitcnt lgkmcnt(0)
	v_mfma_f32_16x16x32_f16 v[60:63], v[162:165], v[180:183], v[60:63]
	v_mfma_f32_16x16x32_f16 v[56:59], v[172:175], v[180:183], v[56:59]
	v_mfma_f32_16x16x32_f16 v[44:47], v[162:165], v[188:191], v[44:47]
	v_mfma_f32_16x16x32_f16 v[40:43], v[172:175], v[188:191], v[40:43]
	v_mfma_f32_16x16x32_f16 v[28:31], v[162:165], v[196:199], v[28:31]
	v_mfma_f32_16x16x32_f16 v[24:27], v[172:175], v[196:199], v[24:27]
	v_mfma_f32_16x16x32_f16 v[12:15], v[162:165], v[204:207], v[12:15]
	v_mfma_f32_16x16x32_f16 v[8:11], v[172:175], v[204:207], v[8:11]
	v_mfma_f32_16x16x32_f16 v[60:63], v[168:171], v[184:187], v[60:63]
	v_mfma_f32_16x16x32_f16 v[56:59], v[176:179], v[184:187], v[56:59]
	v_mfma_f32_16x16x32_f16 v[44:47], v[168:171], v[192:195], v[44:47]
	v_mfma_f32_16x16x32_f16 v[40:43], v[176:179], v[192:195], v[40:43]
	v_mfma_f32_16x16x32_f16 v[28:31], v[168:171], v[200:203], v[28:31]
	v_mfma_f32_16x16x32_f16 v[24:27], v[176:179], v[200:203], v[24:27]
	v_mfma_f32_16x16x32_f16 v[12:15], v[168:171], v[208:211], v[12:15]
	v_mfma_f32_16x16x32_f16 v[8:11], v[176:179], v[208:211], v[8:11]
	s_setprio 0
	s_barrier
	s_add_u32 s28, s28, 0x40080
	s_addc_u32 s29, s29, 0
	s_add_i32 s30, s30, s37
	v_lshl_add_u64 v[162:163], s[28:29], 0, v[148:149]
	s_mov_b32 m0, s30
	s_nop 0
	global_load_lds_dwordx4 v[162:163], off
	v_lshl_add_u64 v[162:163], s[28:29], 0, v[152:153]
	s_add_i32 m0, s30, 0x2000
	s_nop 0
	global_load_lds_dwordx4 v[162:163], off
	s_waitcnt vmcnt(6)
	s_barrier
	s_setprio 1
	v_mfma_f32_16x16x32_f16 v[52:55], v[212:215], v[180:183], v[52:55]
	v_mfma_f32_16x16x32_f16 v[48:51], v[220:223], v[180:183], v[48:51]
	v_mfma_f32_16x16x32_f16 v[36:39], v[212:215], v[188:191], v[36:39]
	v_mfma_f32_16x16x32_f16 v[32:35], v[220:223], v[188:191], v[32:35]
	v_mfma_f32_16x16x32_f16 v[20:23], v[212:215], v[196:199], v[20:23]
	v_mfma_f32_16x16x32_f16 v[16:19], v[220:223], v[196:199], v[16:19]
	v_mfma_f32_16x16x32_f16 v[4:7], v[212:215], v[204:207], v[4:7]
	v_mfma_f32_16x16x32_f16 v[0:3], v[220:223], v[204:207], v[0:3]
	v_mfma_f32_16x16x32_f16 v[52:55], v[216:219], v[184:187], v[52:55]
	v_mfma_f32_16x16x32_f16 v[48:51], v[224:227], v[184:187], v[48:51]
	v_mfma_f32_16x16x32_f16 v[36:39], v[216:219], v[192:195], v[36:39]
	v_mfma_f32_16x16x32_f16 v[32:35], v[224:227], v[192:195], v[32:35]
	v_mfma_f32_16x16x32_f16 v[20:23], v[216:219], v[200:203], v[20:23]
	v_mfma_f32_16x16x32_f16 v[16:19], v[224:227], v[200:203], v[16:19]
	v_mfma_f32_16x16x32_f16 v[4:7], v[216:219], v[208:211], v[4:7]
	v_mfma_f32_16x16x32_f16 v[0:3], v[224:227], v[208:211], v[0:3]
	s_setprio 0
	s_add_i32 s50, s50, 2
	s_add_u32 s26, s26, 0x100
	s_addc_u32 s27, s27, 0
	s_add_u32 s48, s48, 0x100
	s_addc_u32 s49, s49, 0
	s_cmp_gt_u32 s50, 13
	s_barrier
	s_cbranch_scc0 .LBB0_422
	v_lshl_add_u32 v164, s22, 8, v137
	v_ashrrev_i32_e32 v165, 31, v164
	v_readlane_b32 s48, v253, 4
	v_lshl_or_b32 v162, s24, 8, v141
	v_lshlrev_b64 v[168:169], 12, v[164:165]
	v_readlane_b32 s49, v253, 5
	v_ashrrev_i32_e32 v163, 31, v162
	v_lshlrev_b64 v[178:179], 11, v[164:165]
	v_lshl_add_u64 v[168:169], s[48:49], 0, v[168:169]
	v_lshl_add_u64 v[176:177], v[162:163], 2, v[168:169]
	global_load_dwordx4 v[168:171], v[176:177], off
	global_load_dwordx4 v[172:175], v[176:177], off offset:16
	v_lshlrev_b32_e32 v182, 12, v164
	v_lshl_add_u32 v182, v162, 2, v182
	v_add_u32_e32 v183, 0x80000, v182
	global_load_dword v184, v182, s[48:49] offset:512
	v_add_u32_e32 v185, 0x10000, v182
	global_load_dword v186, v185, s[48:49]
	global_load_dword v187, v185, s[48:49] offset:512
	v_add_u32_e32 v188, 0x20000, v182
	global_load_dword v189, v188, s[48:49]
	global_load_dword v190, v188, s[48:49] offset:512
	v_add_u32_e32 v191, 0x30000, v182
	global_load_dword v192, v191, s[48:49]
	global_load_dword v193, v191, s[48:49] offset:512
	global_load_dword v194, v183, s[48:49]
	global_load_dword v195, v183, s[48:49] offset:512
	v_add_u32_e32 v196, 0x10000, v183
	global_load_dword v197, v196, s[48:49]
	global_load_dword v198, v196, s[48:49] offset:512
	v_add_u32_e32 v199, 0x20000, v183
	global_load_dword v200, v199, s[48:49]
	global_load_dword v201, v199, s[48:49] offset:512
	v_add_u32_e32 v202, 0x30000, v183
	global_load_dword v204, v202, s[48:49]
	global_load_dword v205, v202, s[48:49] offset:512
	v_lshl_add_u64 v[178:179], s[10:11], 0, v[178:179]
	v_lshl_add_u64 v[178:179], v[162:163], 1, v[178:179]
	v_readlane_b32 s50, v253, 6
	v_readlane_b32 s51, v253, 7
	v_readlane_b32 s52, v253, 8
	v_readlane_b32 s53, v253, 9
	v_readlane_b32 s54, v253, 10
	v_readlane_b32 s55, v253, 11
	v_readlane_b32 s56, v253, 12
	v_readlane_b32 s57, v253, 13
	v_readlane_b32 s58, v253, 14
	v_readlane_b32 s59, v253, 15
	v_readlane_b32 s60, v253, 16
	v_readlane_b32 s61, v253, 17
	v_readlane_b32 s62, v253, 18
	v_readlane_b32 s63, v253, 19
	s_waitcnt vmcnt(0)
	v_pk_add_f32 v[126:127], v[126:127], v[170:171]
	v_pk_add_f32 v[180:181], v[124:125], v[168:169]
	v_pk_add_f32 v[174:175], v[122:123], v[174:175]
	v_pk_add_f32 v[172:173], v[120:121], v[172:173]
	v_cvt_pk_f16_f32 v123, v174, v175
	v_cvt_pk_f16_f32 v121, v126, v127
	v_cvt_pk_f16_f32 v122, v172, v173
	v_cvt_pk_f16_f32 v120, v180, v181
	global_store_dwordx4 v[178:179], v[120:123], off
	global_load_dwordx4 v[122:125], v[176:177], off offset:512
	s_nop 0
	global_load_dwordx4 v[168:171], v[176:177], off offset:528
	v_mul_f32_e32 v167, v181, v181
	v_fmac_f32_e32 v167, v180, v180
	v_fmac_f32_e32 v167, v126, v126
	v_fmac_f32_e32 v167, v127, v127
	v_fmac_f32_e32 v167, v172, v172
	v_xor_b32_e32 v120, 16, v129
	v_fmac_f32_e32 v167, v173, v173
	v_cmp_lt_i32_e32 vcc, v120, v135
	v_fmac_f32_e32 v167, v174, v174
	v_fmac_f32_e32 v167, v175, v175
	v_cndmask_b32_e32 v120, v129, v120, vcc
	v_lshlrev_b32_e32 v120, 2, v120
	v_xor_b32_e32 v121, 32, v129
	v_cmp_lt_i32_e32 vcc, v121, v135
	s_waitcnt vmcnt(0)
	v_pk_add_f32 v[122:123], v[116:117], v[122:123]
	v_pk_add_f32 v[126:127], v[112:113], v[168:169]
	v_mul_f32_e32 v112, v123, v123
	v_pk_add_f32 v[124:125], v[118:119], v[124:125]
	v_fmac_f32_e32 v112, v122, v122
	v_fmac_f32_e32 v112, v124, v124
	v_fmac_f32_e32 v112, v125, v125
	v_fmac_f32_e32 v112, v126, v126
	v_pk_add_f32 v[116:117], v[114:115], v[170:171]
	v_fmac_f32_e32 v112, v127, v127
	v_fmac_f32_e32 v112, v116, v116
	v_fmac_f32_e32 v112, v117, v117
	v_add_f32_e32 v112, v167, v112
	v_mov_b32_e32 v113, v112
	s_nop 1
	v_permlane16_swap_b32 v112, v113
	v_cndmask_b32_e32 v114, v129, v121, vcc
	v_lshlrev_b32_e32 v114, 2, v114
	v_cvt_pk_f16_f32 v119, v116, v117
	v_cvt_pk_f16_f32 v117, v124, v125
	s_waitcnt lgkmcnt(0)
	v_add_f32_e32 v112, v112, v113
	v_mov_b32_e32 v113, v112
	s_nop 1
	v_permlane32_swap_b32 v112, v113
	v_cvt_pk_f16_f32 v118, v126, v127
	v_cvt_pk_f16_f32 v116, v122, v123
	global_store_dwordx4 v[178:179], v[116:119], off offset:256
	s_and_saveexec_b64 s[22:23], s[6:7]
	s_cbranch_execz .LBB0_425
	v_lshl_add_u64 v[116:117], v[164:165], 2, s[14:15]
	s_waitcnt lgkmcnt(0)
	v_add_f32_e32 v112, v112, v113
	global_atomic_add_f32 v[116:117], v112, off
;     __device__ __forceinline__ void operator()(const f32x4 (&acc)[2][2][4][2], const pg8::Unit& u, int wr, int wc, int fr, int fq) const {
;         const int row0 = u.pm * 256 + wr * 64 + fr, col0 = u.pn * 256 + wc * 32 + 8 * fq;
; #pragma unroll
;         for (int ai = 0; ai < 2; ++ai)
; #pragma unroll
;             for (int m = 0; m < 4; ++m) {
;                 const int row = row0 + ai * 128 + m * 16;
;                 float ss = 0.f, rstd = 1.f;
;                 if (MODE == 2) rstd = rsqrtf(rowss[row] * (1.f / 1024.f) + EPS);
; #pragma unroll
;                 for (int bj = 0; bj < 2; ++bj) {
;                     const int c = col0 + bj * 128;
;                     f32x4 v0 = acc[ai][bj][m][0], v1 = acc[ai][bj][m][1];
;                     if (MODE == 1) {
;                         const float* rp = res + (size_t)row * ldres + c;
;                         v0 += *(const f32x4*)rp; v1 += *(const f32x4*)(rp + 4);
;                     }
;                     if (MODE == 3) {
;                         const h16x8 r8 = *(const h16x8*)(res16 + (size_t)row * ldres + c);
; #pragma unroll
;                         for (int j = 0; j < 4; ++j) { v0[j] += (float)r8[j]; v1[j] += (float)r8[4 + j]; }
;                     }
;                     if (MODE == 1 || MODE == 3) {
;                         ss += v0[0] * v0[0] + v0[1] * v0[1] + v0[2] * v0[2] + v0[3] * v0[3] + v1[0] * v1[0] + v1[1] * v1[1] + v1[2] * v1[2] + v1[3] * v1[3];
;                     }
;                     if (MODE == 2) {
; #pragma unroll
;                         for (int j = 0; j < 4; ++j) { float a = fmaxf(v0[j] * rstd, 0.f), b = fmaxf(v1[j] * rstd, 0.f); v0[j] = a * a; v1[j] = b * b; }
;                     }
;                     *(h16x8*)(o16 + (size_t)row * ld16 + c) = pack8(v0, v1);
;                 }
;                 if (MODE == 1 || MODE == 3) {
;                     ss += __shfl_xor(ss, 16); ss += __shfl_xor(ss, 32);
;                     if (fq == 0) atomicAdd(rowss + row, ss);
.LBB0_425:
	s_or_b64 exec, exec, s[22:23]
	v_or_b32_e32 v112, 16, v164
	s_waitcnt lgkmcnt(0)
	v_ashrrev_i32_e32 v113, 31, v112
	v_readlane_b32 s48, v253, 4
	v_lshlrev_b64 v[116:117], 12, v[112:113]
	v_readlane_b32 s49, v253, 5
	v_lshlrev_b64 v[168:169], 11, v[112:113]
	v_lshl_add_u64 v[168:169], s[10:11], 0, v[168:169]
	v_lshl_add_u64 v[116:117], s[48:49], 0, v[116:117]
	v_lshl_add_u64 v[126:127], v[162:163], 2, v[116:117]
	global_load_dwordx4 v[116:119], v[126:127], off
	global_load_dwordx4 v[122:125], v[126:127], off offset:16
	v_lshl_add_u64 v[168:169], v[162:163], 1, v[168:169]
	v_readlane_b32 s60, v253, 16
	v_readlane_b32 s61, v253, 17
	v_readlane_b32 s62, v253, 18
	v_readlane_b32 s63, v253, 19
	v_readlane_b32 s50, v253, 6
	v_readlane_b32 s51, v253, 7
	v_readlane_b32 s52, v253, 8
	v_readlane_b32 s53, v253, 9
	v_readlane_b32 s54, v253, 10
	v_readlane_b32 s55, v253, 11
	v_readlane_b32 s56, v253, 12
	v_readlane_b32 s57, v253, 13
	v_readlane_b32 s58, v253, 14
	v_readlane_b32 s59, v253, 15
	s_waitcnt vmcnt(1)
	v_pk_add_f32 v[118:119], v[110:111], v[118:119]
	v_pk_add_f32 v[116:117], v[108:109], v[116:117]
	s_waitcnt vmcnt(0)
	v_pk_add_f32 v[124:125], v[106:107], v[124:125]
	v_pk_add_f32 v[122:123], v[104:105], v[122:123]
	v_cvt_pk_f16_f32 v107, v124, v125
	v_cvt_pk_f16_f32 v105, v118, v119
	v_cvt_pk_f16_f32 v106, v122, v123
	v_cvt_pk_f16_f32 v104, v116, v117
	global_store_dwordx4 v[168:169], v[104:107], off
	global_load_dwordx4 v[104:107], v[126:127], off offset:512
	s_nop 0
	global_load_dwordx4 v[108:111], v[126:127], off offset:528
	v_mul_f32_e32 v115, v117, v117
	v_fmac_f32_e32 v115, v116, v116
	v_fmac_f32_e32 v115, v118, v118
	v_fmac_f32_e32 v115, v119, v119
	v_fmac_f32_e32 v115, v122, v122
	v_fmac_f32_e32 v115, v123, v123
	v_fmac_f32_e32 v115, v124, v124
	v_fmac_f32_e32 v115, v125, v125
	s_waitcnt vmcnt(1)
	v_pk_add_f32 v[104:105], v[100:101], v[104:105]
	v_pk_add_f32 v[102:103], v[102:103], v[106:107]
	s_waitcnt vmcnt(0)
	v_pk_add_f32 v[106:107], v[96:97], v[108:109]
	v_mul_f32_e32 v96, v105, v105
	v_fmac_f32_e32 v96, v104, v104
	v_fmac_f32_e32 v96, v102, v102
	v_fmac_f32_e32 v96, v103, v103
	v_fmac_f32_e32 v96, v106, v106
	v_pk_add_f32 v[98:99], v[98:99], v[110:111]
	v_fmac_f32_e32 v96, v107, v107
	v_fmac_f32_e32 v96, v98, v98
	v_fmac_f32_e32 v96, v99, v99
	v_add_f32_e32 v96, v115, v96
	v_mov_b32_e32 v97, v96
	s_nop 1
	v_permlane16_swap_b32 v96, v97
	v_cvt_pk_f16_f32 v101, v98, v99
	v_cvt_pk_f16_f32 v99, v102, v103
	v_cvt_pk_f16_f32 v100, v106, v107
	v_cvt_pk_f16_f32 v98, v104, v105
	s_waitcnt lgkmcnt(0)
	v_add_f32_e32 v96, v96, v97
	v_mov_b32_e32 v97, v96
	s_nop 1
	v_permlane32_swap_b32 v96, v97
	global_store_dwordx4 v[168:169], v[98:101], off offset:256
	s_and_saveexec_b64 s[22:23], s[6:7]
	v_readlane_b32 s48, v253, 20
	v_readlane_b32 s60, v253, 32
	v_readlane_b32 s61, v253, 33
	v_readlane_b32 s62, v253, 34
	v_readlane_b32 s63, v253, 35
	v_readlane_b32 s49, v253, 21
	v_readlane_b32 s50, v253, 22
	v_readlane_b32 s51, v253, 23
	v_readlane_b32 s52, v253, 24
	v_readlane_b32 s53, v253, 25
	v_readlane_b32 s54, v253, 26
	v_readlane_b32 s55, v253, 27
	v_readlane_b32 s56, v253, 28
	v_readlane_b32 s57, v253, 29
	v_readlane_b32 s58, v253, 30
	v_readlane_b32 s59, v253, 31
	s_cbranch_execz .LBB0_427
	v_lshl_add_u64 v[98:99], v[112:113], 2, s[14:15]
	s_waitcnt lgkmcnt(0)
	v_add_f32_e32 v96, v96, v97
	global_atomic_add_f32 v[98:99], v96, off
.LBB0_427:
	s_or_b64 exec, exec, s[22:23]
	v_or_b32_e32 v96, 32, v164
	s_waitcnt lgkmcnt(0)
	v_ashrrev_i32_e32 v97, 31, v96
	v_readlane_b32 s64, v253, 4
	v_lshlrev_b64 v[98:99], 12, v[96:97]
	v_readlane_b32 s65, v253, 5
	v_lshlrev_b64 v[108:109], 11, v[96:97]
	v_lshl_add_u64 v[108:109], s[10:11], 0, v[108:109]
	v_lshl_add_u64 v[98:99], s[64:65], 0, v[98:99]
	v_lshl_add_u64 v[106:107], v[162:163], 2, v[98:99]
	global_load_dwordx4 v[98:101], v[106:107], off
	global_load_dwordx4 v[102:105], v[106:107], off offset:16
	v_lshl_add_u64 v[108:109], v[162:163], 1, v[108:109]
	v_readlane_b32 s66, v253, 6
	v_readlane_b32 s67, v253, 7
	v_readlane_b32 s68, v253, 8
	v_readlane_b32 s69, v253, 9
	v_readlane_b32 s70, v253, 10
	v_readlane_b32 s71, v253, 11
	v_readlane_b32 s72, v253, 12
	v_readlane_b32 s73, v253, 13
	v_readlane_b32 s74, v253, 14
	v_readlane_b32 s75, v253, 15
	v_readlane_b32 s76, v253, 16
	v_readlane_b32 s77, v253, 17
	v_readlane_b32 s78, v253, 18
	v_readlane_b32 s79, v253, 19
	s_waitcnt vmcnt(1)
	v_pk_add_f32 v[100:101], v[94:95], v[100:101]
	v_pk_add_f32 v[98:99], v[92:93], v[98:99]
	s_waitcnt vmcnt(0)
	v_pk_add_f32 v[104:105], v[90:91], v[104:105]
	v_pk_add_f32 v[102:103], v[88:89], v[102:103]
	v_cvt_pk_f16_f32 v91, v104, v105
	v_cvt_pk_f16_f32 v89, v100, v101
	v_cvt_pk_f16_f32 v90, v102, v103
	v_cvt_pk_f16_f32 v88, v98, v99
	global_store_dwordx4 v[108:109], v[88:91], off
	global_load_dwordx4 v[88:91], v[106:107], off offset:512
	s_nop 0
	global_load_dwordx4 v[92:95], v[106:107], off offset:528
	v_mul_f32_e32 v99, v99, v99
	v_fmac_f32_e32 v99, v98, v98
	v_fmac_f32_e32 v99, v100, v100
	v_fmac_f32_e32 v99, v101, v101
	v_fmac_f32_e32 v99, v102, v102
	v_fmac_f32_e32 v99, v103, v103
	v_fmac_f32_e32 v99, v104, v104
	v_fmac_f32_e32 v99, v105, v105
	s_waitcnt vmcnt(1)
	v_pk_add_f32 v[88:89], v[84:85], v[88:89]
	v_pk_add_f32 v[86:87], v[86:87], v[90:91]
	s_waitcnt vmcnt(0)
	v_pk_add_f32 v[90:91], v[80:81], v[92:93]
	v_mul_f32_e32 v80, v89, v89
	v_fmac_f32_e32 v80, v88, v88
	v_fmac_f32_e32 v80, v86, v86
	v_fmac_f32_e32 v80, v87, v87
	v_fmac_f32_e32 v80, v90, v90
	v_pk_add_f32 v[82:83], v[82:83], v[94:95]
	v_fmac_f32_e32 v80, v91, v91
	v_fmac_f32_e32 v80, v82, v82
	v_fmac_f32_e32 v80, v83, v83
	v_add_f32_e32 v80, v99, v80
	v_mov_b32_e32 v81, v80
	s_nop 1
	v_permlane16_swap_b32 v80, v81
	v_cvt_pk_f16_f32 v85, v82, v83
	v_cvt_pk_f16_f32 v83, v86, v87
	v_cvt_pk_f16_f32 v84, v90, v91
	v_cvt_pk_f16_f32 v82, v88, v89
	s_waitcnt lgkmcnt(0)
	v_add_f32_e32 v80, v80, v81
	v_mov_b32_e32 v81, v80
	s_nop 1
	v_permlane32_swap_b32 v80, v81
	global_store_dwordx4 v[108:109], v[82:85], off offset:256
	s_and_saveexec_b64 s[22:23], s[6:7]
	s_cbranch_execz .LBB0_429
	v_lshl_add_u64 v[82:83], v[96:97], 2, s[14:15]
	s_waitcnt lgkmcnt(0)
	v_add_f32_e32 v80, v80, v81
	global_atomic_add_f32 v[82:83], v80, off
;     __device__ __forceinline__ void operator()(const f32x4 (&acc)[2][2][4][2], const pg8::Unit& u, int wr, int wc, int fr, int fq) const {
;     ...
;                     const int c = col0 + bj * 128;
;                     f32x4 v0 = acc[ai][bj][m][0], v1 = acc[ai][bj][m][1];
;                     if (MODE == 1) {
;                         const float* rp = res + (size_t)row * ldres + c;
;                         v0 += *(const f32x4*)rp; v1 += *(const f32x4*)(rp + 4);
;                     }
;                     if (MODE == 3) {
;                         const h16x8 r8 = *(const h16x8*)(res16 + (size_t)row * ldres + c);
; #pragma unroll
;                         for (int j = 0; j < 4; ++j) { v0[j] += (float)r8[j]; v1[j] += (float)r8[4 + j]; }
;                     }
;                     if (MODE == 1 || MODE == 3) {
;                         ss += v0[0] * v0[0] + v0[1] * v0[1] + v0[2] * v0[2] + v0[3] * v0[3] + v1[0] * v1[0] + v1[1] * v1[1] + v1[2] * v1[2] + v1[3] * v1[3];
;                     }
;                     if (MODE == 2) {
; #pragma unroll
;                         for (int j = 0; j < 4; ++j) { float a = fmaxf(v0[j] * rstd, 0.f), b = fmaxf(v1[j] * rstd, 0.f); v0[j] = a * a; v1[j] = b * b; }
;                     }
;                     *(h16x8*)(o16 + (size_t)row * ld16 + c) = pack8(v0, v1);
;                 }
;                 if (MODE == 1 || MODE == 3) {
;                     ss += __shfl_xor(ss, 16); ss += __shfl_xor(ss, 32);
;                     if (fq == 0) atomicAdd(rowss + row, ss);
.LBB0_429:
	s_or_b64 exec, exec, s[22:23]
	v_or_b32_e32 v80, 48, v164
	s_waitcnt lgkmcnt(0)
	v_ashrrev_i32_e32 v81, 31, v80
	v_readlane_b32 s64, v253, 4
	v_lshlrev_b64 v[82:83], 12, v[80:81]
	v_readlane_b32 s65, v253, 5
	v_lshlrev_b64 v[92:93], 11, v[80:81]
	v_lshl_add_u64 v[92:93], s[10:11], 0, v[92:93]
	v_lshl_add_u64 v[82:83], s[64:65], 0, v[82:83]
	v_lshl_add_u64 v[90:91], v[162:163], 2, v[82:83]
	global_load_dwordx4 v[82:85], v[90:91], off
	global_load_dwordx4 v[86:89], v[90:91], off offset:16
	v_lshl_add_u64 v[92:93], v[162:163], 1, v[92:93]
	v_readlane_b32 s66, v253, 6
	v_readlane_b32 s67, v253, 7
	v_readlane_b32 s68, v253, 8
	v_readlane_b32 s69, v253, 9
	v_readlane_b32 s70, v253, 10
	v_readlane_b32 s71, v253, 11
	v_readlane_b32 s72, v253, 12
	v_readlane_b32 s73, v253, 13
	v_readlane_b32 s74, v253, 14
	v_readlane_b32 s75, v253, 15
	v_readlane_b32 s76, v253, 16
	v_readlane_b32 s77, v253, 17
	v_readlane_b32 s78, v253, 18
	v_readlane_b32 s79, v253, 19
	s_waitcnt vmcnt(1)
	v_pk_add_f32 v[84:85], v[78:79], v[84:85]
	v_pk_add_f32 v[82:83], v[76:77], v[82:83]
	s_waitcnt vmcnt(0)
	v_pk_add_f32 v[88:89], v[74:75], v[88:89]
	v_pk_add_f32 v[86:87], v[72:73], v[86:87]
	v_cvt_pk_f16_f32 v75, v88, v89
	v_cvt_pk_f16_f32 v73, v84, v85
	v_cvt_pk_f16_f32 v74, v86, v87
	v_cvt_pk_f16_f32 v72, v82, v83
	global_store_dwordx4 v[92:93], v[72:75], off
	global_load_dwordx4 v[72:75], v[90:91], off offset:512
	s_nop 0
	global_load_dwordx4 v[76:79], v[90:91], off offset:528
	v_mul_f32_e32 v83, v83, v83
	v_fmac_f32_e32 v83, v82, v82
	v_fmac_f32_e32 v83, v84, v84
	v_fmac_f32_e32 v83, v85, v85
	v_fmac_f32_e32 v83, v86, v86
	v_fmac_f32_e32 v83, v87, v87
	v_fmac_f32_e32 v83, v88, v88
	v_fmac_f32_e32 v83, v89, v89
	s_waitcnt vmcnt(1)
	v_pk_add_f32 v[72:73], v[68:69], v[72:73]
	v_pk_add_f32 v[70:71], v[70:71], v[74:75]
	s_waitcnt vmcnt(0)
	v_pk_add_f32 v[74:75], v[64:65], v[76:77]
	v_mul_f32_e32 v64, v73, v73
	v_fmac_f32_e32 v64, v72, v72
	v_fmac_f32_e32 v64, v70, v70
	v_fmac_f32_e32 v64, v71, v71
	v_fmac_f32_e32 v64, v74, v74
	v_pk_add_f32 v[66:67], v[66:67], v[78:79]
	v_fmac_f32_e32 v64, v75, v75
	v_fmac_f32_e32 v64, v66, v66
	v_fmac_f32_e32 v64, v67, v67
	v_add_f32_e32 v64, v83, v64
	v_mov_b32_e32 v65, v64
	s_nop 1
	v_permlane16_swap_b32 v64, v65
	v_cvt_pk_f16_f32 v69, v66, v67
	v_cvt_pk_f16_f32 v67, v70, v71
	v_cvt_pk_f16_f32 v68, v74, v75
	v_cvt_pk_f16_f32 v66, v72, v73
	s_waitcnt lgkmcnt(0)
	v_add_f32_e32 v64, v64, v65
	v_mov_b32_e32 v65, v64
	s_nop 1
	v_permlane32_swap_b32 v64, v65
	global_store_dwordx4 v[92:93], v[66:69], off offset:256
	s_and_saveexec_b64 s[22:23], s[6:7]
	s_cbranch_execz .LBB0_431
	v_lshl_add_u64 v[66:67], v[80:81], 2, s[14:15]
	s_waitcnt lgkmcnt(0)
	v_add_f32_e32 v64, v64, v65
	global_atomic_add_f32 v[66:67], v64, off
.LBB0_431:
	s_or_b64 exec, exec, s[22:23]
	v_add_u32_e32 v64, 0x80, v164
	s_waitcnt lgkmcnt(0)
	v_ashrrev_i32_e32 v65, 31, v64
	v_readlane_b32 s64, v253, 4
	v_lshlrev_b64 v[66:67], 12, v[64:65]
	v_readlane_b32 s65, v253, 5
	v_lshlrev_b64 v[76:77], 11, v[64:65]
	v_lshl_add_u64 v[76:77], s[10:11], 0, v[76:77]
	v_lshl_add_u64 v[66:67], s[64:65], 0, v[66:67]
	v_lshl_add_u64 v[74:75], v[162:163], 2, v[66:67]
	global_load_dwordx4 v[66:69], v[74:75], off
	global_load_dwordx4 v[70:73], v[74:75], off offset:16
	v_lshl_add_u64 v[76:77], v[162:163], 1, v[76:77]
	v_readlane_b32 s66, v253, 6
	v_readlane_b32 s67, v253, 7
	v_readlane_b32 s68, v253, 8
	v_readlane_b32 s69, v253, 9
	v_readlane_b32 s70, v253, 10
	v_readlane_b32 s71, v253, 11
	v_readlane_b32 s72, v253, 12
	v_readlane_b32 s73, v253, 13
	v_readlane_b32 s74, v253, 14
	v_readlane_b32 s75, v253, 15
	v_readlane_b32 s76, v253, 16
	v_readlane_b32 s77, v253, 17
	v_readlane_b32 s78, v253, 18
	v_readlane_b32 s79, v253, 19
	s_waitcnt vmcnt(1)
	v_pk_add_f32 v[68:69], v[62:63], v[68:69]
	v_pk_add_f32 v[66:67], v[60:61], v[66:67]
	s_waitcnt vmcnt(0)
	v_pk_add_f32 v[72:73], v[58:59], v[72:73]
	v_pk_add_f32 v[70:71], v[56:57], v[70:71]
	v_cvt_pk_f16_f32 v59, v72, v73
	v_cvt_pk_f16_f32 v57, v68, v69
	v_cvt_pk_f16_f32 v58, v70, v71
	v_cvt_pk_f16_f32 v56, v66, v67
	global_store_dwordx4 v[76:77], v[56:59], off
	global_load_dwordx4 v[56:59], v[74:75], off offset:512
	s_nop 0
	global_load_dwordx4 v[60:63], v[74:75], off offset:528
	v_mul_f32_e32 v67, v67, v67
	v_fmac_f32_e32 v67, v66, v66
	v_fmac_f32_e32 v67, v68, v68
	v_fmac_f32_e32 v67, v69, v69
	v_fmac_f32_e32 v67, v70, v70
	v_fmac_f32_e32 v67, v71, v71
	v_fmac_f32_e32 v67, v72, v72
	v_fmac_f32_e32 v67, v73, v73
	s_waitcnt vmcnt(1)
	v_pk_add_f32 v[56:57], v[52:53], v[56:57]
	v_pk_add_f32 v[54:55], v[54:55], v[58:59]
	s_waitcnt vmcnt(0)
	v_pk_add_f32 v[58:59], v[48:49], v[60:61]
	v_mul_f32_e32 v48, v57, v57
	v_fmac_f32_e32 v48, v56, v56
	v_fmac_f32_e32 v48, v54, v54
	v_fmac_f32_e32 v48, v55, v55
	v_fmac_f32_e32 v48, v58, v58
	v_pk_add_f32 v[50:51], v[50:51], v[62:63]
	v_fmac_f32_e32 v48, v59, v59
	v_fmac_f32_e32 v48, v50, v50
	v_fmac_f32_e32 v48, v51, v51
	v_add_f32_e32 v48, v67, v48
	v_mov_b32_e32 v49, v48
	s_nop 1
	v_permlane16_swap_b32 v48, v49
	v_cvt_pk_f16_f32 v53, v50, v51
	v_cvt_pk_f16_f32 v51, v54, v55
	v_cvt_pk_f16_f32 v52, v58, v59
	v_cvt_pk_f16_f32 v50, v56, v57
	s_waitcnt lgkmcnt(0)
	v_add_f32_e32 v48, v48, v49
	v_mov_b32_e32 v49, v48
	s_nop 1
	v_permlane32_swap_b32 v48, v49
	global_store_dwordx4 v[76:77], v[50:53], off offset:256
	s_and_saveexec_b64 s[22:23], s[6:7]
	s_cbranch_execz .LBB0_433
	v_lshl_add_u64 v[50:51], v[64:65], 2, s[14:15]
	s_waitcnt lgkmcnt(0)
	v_add_f32_e32 v48, v48, v49
	global_atomic_add_f32 v[50:51], v48, off
;     __device__ __forceinline__ void operator()(const f32x4 (&acc)[2][2][4][2], const pg8::Unit& u, int wr, int wc, int fr, int fq) const {
;     ...
;                     const int c = col0 + bj * 128;
;                     f32x4 v0 = acc[ai][bj][m][0], v1 = acc[ai][bj][m][1];
;                     if (MODE == 1) {
;                         const float* rp = res + (size_t)row * ldres + c;
;                         v0 += *(const f32x4*)rp; v1 += *(const f32x4*)(rp + 4);
;                     }
;                     if (MODE == 3) {
;                         const h16x8 r8 = *(const h16x8*)(res16 + (size_t)row * ldres + c);
; #pragma unroll
;                         for (int j = 0; j < 4; ++j) { v0[j] += (float)r8[j]; v1[j] += (float)r8[4 + j]; }
;                     }
;                     if (MODE == 1 || MODE == 3) {
;                         ss += v0[0] * v0[0] + v0[1] * v0[1] + v0[2] * v0[2] + v0[3] * v0[3] + v1[0] * v1[0] + v1[1] * v1[1] + v1[2] * v1[2] + v1[3] * v1[3];
;                     }
;                     if (MODE == 2) {
; #pragma unroll
;                         for (int j = 0; j < 4; ++j) { float a = fmaxf(v0[j] * rstd, 0.f), b = fmaxf(v1[j] * rstd, 0.f); v0[j] = a * a; v1[j] = b * b; }
;                     }
;                     *(h16x8*)(o16 + (size_t)row * ld16 + c) = pack8(v0, v1);
;                 }
;                 if (MODE == 1 || MODE == 3) {
;                     ss += __shfl_xor(ss, 16); ss += __shfl_xor(ss, 32);
;                     if (fq == 0) atomicAdd(rowss + row, ss);
.LBB0_433:
	s_or_b64 exec, exec, s[22:23]
	v_add_u32_e32 v48, 0x90, v164
	s_waitcnt lgkmcnt(0)
	v_ashrrev_i32_e32 v49, 31, v48
	v_readlane_b32 s64, v253, 4
	v_lshlrev_b64 v[50:51], 12, v[48:49]
	v_readlane_b32 s65, v253, 5
	v_lshlrev_b64 v[60:61], 11, v[48:49]
	v_lshl_add_u64 v[60:61], s[10:11], 0, v[60:61]
	v_lshl_add_u64 v[50:51], s[64:65], 0, v[50:51]
	v_lshl_add_u64 v[58:59], v[162:163], 2, v[50:51]
	global_load_dwordx4 v[50:53], v[58:59], off
	global_load_dwordx4 v[54:57], v[58:59], off offset:16
	v_lshl_add_u64 v[60:61], v[162:163], 1, v[60:61]
	v_readlane_b32 s66, v253, 6
	v_readlane_b32 s67, v253, 7
	v_readlane_b32 s68, v253, 8
	v_readlane_b32 s69, v253, 9
	v_readlane_b32 s70, v253, 10
	v_readlane_b32 s71, v253, 11
	v_readlane_b32 s72, v253, 12
	v_readlane_b32 s73, v253, 13
	v_readlane_b32 s74, v253, 14
	v_readlane_b32 s75, v253, 15
	v_readlane_b32 s76, v253, 16
	v_readlane_b32 s77, v253, 17
	v_readlane_b32 s78, v253, 18
	v_readlane_b32 s79, v253, 19
	s_waitcnt vmcnt(1)
	v_pk_add_f32 v[52:53], v[46:47], v[52:53]
	v_pk_add_f32 v[50:51], v[44:45], v[50:51]
	s_waitcnt vmcnt(0)
	v_pk_add_f32 v[56:57], v[42:43], v[56:57]
	v_pk_add_f32 v[54:55], v[40:41], v[54:55]
	v_cvt_pk_f16_f32 v43, v56, v57
	v_cvt_pk_f16_f32 v41, v52, v53
	v_cvt_pk_f16_f32 v42, v54, v55
	v_cvt_pk_f16_f32 v40, v50, v51
	global_store_dwordx4 v[60:61], v[40:43], off
	global_load_dwordx4 v[40:43], v[58:59], off offset:512
	s_nop 0
	global_load_dwordx4 v[44:47], v[58:59], off offset:528
	v_mul_f32_e32 v51, v51, v51
	v_fmac_f32_e32 v51, v50, v50
	v_fmac_f32_e32 v51, v52, v52
	v_fmac_f32_e32 v51, v53, v53
	v_fmac_f32_e32 v51, v54, v54
	v_fmac_f32_e32 v51, v55, v55
	v_fmac_f32_e32 v51, v56, v56
	v_fmac_f32_e32 v51, v57, v57
	s_waitcnt vmcnt(1)
	v_pk_add_f32 v[40:41], v[36:37], v[40:41]
	v_pk_add_f32 v[38:39], v[38:39], v[42:43]
	s_waitcnt vmcnt(0)
	v_pk_add_f32 v[42:43], v[32:33], v[44:45]
	v_mul_f32_e32 v32, v41, v41
	v_fmac_f32_e32 v32, v40, v40
	v_fmac_f32_e32 v32, v38, v38
	v_fmac_f32_e32 v32, v39, v39
	v_fmac_f32_e32 v32, v42, v42
	v_pk_add_f32 v[34:35], v[34:35], v[46:47]
	v_fmac_f32_e32 v32, v43, v43
	v_fmac_f32_e32 v32, v34, v34
	v_fmac_f32_e32 v32, v35, v35
	v_add_f32_e32 v32, v51, v32
	v_mov_b32_e32 v33, v32
	s_nop 1
	v_permlane16_swap_b32 v32, v33
	v_cvt_pk_f16_f32 v37, v34, v35
	v_cvt_pk_f16_f32 v35, v38, v39
	v_cvt_pk_f16_f32 v36, v42, v43
	v_cvt_pk_f16_f32 v34, v40, v41
	s_waitcnt lgkmcnt(0)
	v_add_f32_e32 v32, v32, v33
	v_mov_b32_e32 v33, v32
	s_nop 1
	v_permlane32_swap_b32 v32, v33
	global_store_dwordx4 v[60:61], v[34:37], off offset:256
	s_and_saveexec_b64 s[22:23], s[6:7]
	s_cbranch_execz .LBB0_435
	v_lshl_add_u64 v[34:35], v[48:49], 2, s[14:15]
	s_waitcnt lgkmcnt(0)
	v_add_f32_e32 v32, v32, v33
	global_atomic_add_f32 v[34:35], v32, off
;     __device__ __forceinline__ void operator()(const f32x4 (&acc)[2][2][4][2], const pg8::Unit& u, int wr, int wc, int fr, int fq) const {
;     ...
;                     const int c = col0 + bj * 128;
;                     f32x4 v0 = acc[ai][bj][m][0], v1 = acc[ai][bj][m][1];
;                     if (MODE == 1) {
;                         const float* rp = res + (size_t)row * ldres + c;
;                         v0 += *(const f32x4*)rp; v1 += *(const f32x4*)(rp + 4);
;                     }
;                     if (MODE == 3) {
;                         const h16x8 r8 = *(const h16x8*)(res16 + (size_t)row * ldres + c);
; #pragma unroll
;                         for (int j = 0; j < 4; ++j) { v0[j] += (float)r8[j]; v1[j] += (float)r8[4 + j]; }
;                     }
;                     if (MODE == 1 || MODE == 3) {
;                         ss += v0[0] * v0[0] + v0[1] * v0[1] + v0[2] * v0[2] + v0[3] * v0[3] + v1[0] * v1[0] + v1[1] * v1[1] + v1[2] * v1[2] + v1[3] * v1[3];
;                     }
;                     if (MODE == 2) {
; #pragma unroll
;                         for (int j = 0; j < 4; ++j) { float a = fmaxf(v0[j] * rstd, 0.f), b = fmaxf(v1[j] * rstd, 0.f); v0[j] = a * a; v1[j] = b * b; }
;                     }
;                     *(h16x8*)(o16 + (size_t)row * ld16 + c) = pack8(v0, v1);
;                 }
;                 if (MODE == 1 || MODE == 3) {
;                     ss += __shfl_xor(ss, 16); ss += __shfl_xor(ss, 32);
;                     if (fq == 0) atomicAdd(rowss + row, ss);
.LBB0_435:
	s_or_b64 exec, exec, s[22:23]
	v_add_u32_e32 v32, 0xa0, v164
	s_waitcnt lgkmcnt(0)
	v_ashrrev_i32_e32 v33, 31, v32
	v_readlane_b32 s64, v253, 4
	v_lshlrev_b64 v[34:35], 12, v[32:33]
	v_readlane_b32 s65, v253, 5
	v_lshlrev_b64 v[44:45], 11, v[32:33]
	v_lshl_add_u64 v[44:45], s[10:11], 0, v[44:45]
	v_lshl_add_u64 v[34:35], s[64:65], 0, v[34:35]
	v_lshl_add_u64 v[42:43], v[162:163], 2, v[34:35]
	global_load_dwordx4 v[34:37], v[42:43], off
	global_load_dwordx4 v[38:41], v[42:43], off offset:16
	v_lshl_add_u64 v[44:45], v[162:163], 1, v[44:45]
	v_readlane_b32 s66, v253, 6
	v_readlane_b32 s67, v253, 7
	v_readlane_b32 s68, v253, 8
	v_readlane_b32 s69, v253, 9
	v_readlane_b32 s70, v253, 10
	v_readlane_b32 s71, v253, 11
	v_readlane_b32 s72, v253, 12
	v_readlane_b32 s73, v253, 13
	v_readlane_b32 s74, v253, 14
	v_readlane_b32 s75, v253, 15
	v_readlane_b32 s76, v253, 16
	v_readlane_b32 s77, v253, 17
	v_readlane_b32 s78, v253, 18
	v_readlane_b32 s79, v253, 19
	s_waitcnt vmcnt(1)
	v_pk_add_f32 v[36:37], v[30:31], v[36:37]
	v_pk_add_f32 v[34:35], v[28:29], v[34:35]
	s_waitcnt vmcnt(0)
	v_pk_add_f32 v[40:41], v[26:27], v[40:41]
	v_pk_add_f32 v[38:39], v[24:25], v[38:39]
	v_cvt_pk_f16_f32 v27, v40, v41
	v_cvt_pk_f16_f32 v25, v36, v37
	v_cvt_pk_f16_f32 v26, v38, v39
	v_cvt_pk_f16_f32 v24, v34, v35
	global_store_dwordx4 v[44:45], v[24:27], off
	global_load_dwordx4 v[24:27], v[42:43], off offset:512
	s_nop 0
	global_load_dwordx4 v[28:31], v[42:43], off offset:528
	v_mul_f32_e32 v35, v35, v35
	v_fmac_f32_e32 v35, v34, v34
	v_fmac_f32_e32 v35, v36, v36
	v_fmac_f32_e32 v35, v37, v37
	v_fmac_f32_e32 v35, v38, v38
	v_fmac_f32_e32 v35, v39, v39
	v_fmac_f32_e32 v35, v40, v40
	v_fmac_f32_e32 v35, v41, v41
	s_waitcnt vmcnt(1)
	v_pk_add_f32 v[24:25], v[20:21], v[24:25]
	v_pk_add_f32 v[22:23], v[22:23], v[26:27]
	s_waitcnt vmcnt(0)
	v_pk_add_f32 v[26:27], v[16:17], v[28:29]
	v_mul_f32_e32 v16, v25, v25
	v_fmac_f32_e32 v16, v24, v24
	v_fmac_f32_e32 v16, v22, v22
	v_fmac_f32_e32 v16, v23, v23
	v_fmac_f32_e32 v16, v26, v26
	v_pk_add_f32 v[18:19], v[18:19], v[30:31]
	v_fmac_f32_e32 v16, v27, v27
	v_fmac_f32_e32 v16, v18, v18
	v_fmac_f32_e32 v16, v19, v19
	v_add_f32_e32 v16, v35, v16
	v_mov_b32_e32 v17, v16
	s_nop 1
	v_permlane16_swap_b32 v16, v17
	v_cvt_pk_f16_f32 v21, v18, v19
	v_cvt_pk_f16_f32 v19, v22, v23
	v_cvt_pk_f16_f32 v20, v26, v27
	v_cvt_pk_f16_f32 v18, v24, v25
	s_waitcnt lgkmcnt(0)
	v_add_f32_e32 v16, v16, v17
	v_mov_b32_e32 v17, v16
	s_nop 1
	v_permlane32_swap_b32 v16, v17
	global_store_dwordx4 v[44:45], v[18:21], off offset:256
	s_and_saveexec_b64 s[22:23], s[6:7]
	s_cbranch_execz .LBB0_437
	v_lshl_add_u64 v[18:19], v[32:33], 2, s[14:15]
	s_waitcnt lgkmcnt(0)
	v_add_f32_e32 v16, v16, v17
	global_atomic_add_f32 v[18:19], v16, off
.LBB0_437:
	s_or_b64 exec, exec, s[22:23]
	v_add_u32_e32 v16, 0xb0, v164
	s_waitcnt lgkmcnt(0)
	v_ashrrev_i32_e32 v17, 31, v16
	v_readlane_b32 s64, v253, 4
	v_lshlrev_b64 v[18:19], 12, v[16:17]
	v_readlane_b32 s65, v253, 5
	v_lshlrev_b64 v[28:29], 11, v[16:17]
	v_lshl_add_u64 v[28:29], s[10:11], 0, v[28:29]
	v_lshl_add_u64 v[18:19], s[64:65], 0, v[18:19]
	v_lshl_add_u64 v[26:27], v[162:163], 2, v[18:19]
	global_load_dwordx4 v[18:21], v[26:27], off
	global_load_dwordx4 v[22:25], v[26:27], off offset:16
	v_lshl_add_u64 v[28:29], v[162:163], 1, v[28:29]
	v_readlane_b32 s66, v253, 6
	v_readlane_b32 s67, v253, 7
	v_readlane_b32 s68, v253, 8
	v_readlane_b32 s69, v253, 9
	v_readlane_b32 s70, v253, 10
	v_readlane_b32 s71, v253, 11
	v_readlane_b32 s72, v253, 12
	v_readlane_b32 s73, v253, 13
	v_readlane_b32 s74, v253, 14
	v_readlane_b32 s75, v253, 15
	v_readlane_b32 s76, v253, 16
	v_readlane_b32 s77, v253, 17
	v_readlane_b32 s78, v253, 18
	v_readlane_b32 s79, v253, 19
	s_waitcnt vmcnt(1)
	v_pk_add_f32 v[20:21], v[14:15], v[20:21]
	v_pk_add_f32 v[18:19], v[12:13], v[18:19]
	s_waitcnt vmcnt(0)
	v_pk_add_f32 v[24:25], v[10:11], v[24:25]
	v_pk_add_f32 v[22:23], v[8:9], v[22:23]
	v_cvt_pk_f16_f32 v11, v24, v25
	v_cvt_pk_f16_f32 v9, v20, v21
	v_cvt_pk_f16_f32 v10, v22, v23
	v_cvt_pk_f16_f32 v8, v18, v19
	global_store_dwordx4 v[28:29], v[8:11], off
	global_load_dwordx4 v[8:11], v[26:27], off offset:512
	s_nop 0
	global_load_dwordx4 v[12:15], v[26:27], off offset:528
	v_mul_f32_e32 v19, v19, v19
	v_fmac_f32_e32 v19, v18, v18
	v_fmac_f32_e32 v19, v20, v20
	v_fmac_f32_e32 v19, v21, v21
	v_fmac_f32_e32 v19, v22, v22
	v_fmac_f32_e32 v19, v23, v23
	v_fmac_f32_e32 v19, v24, v24
	v_fmac_f32_e32 v19, v25, v25
	s_waitcnt vmcnt(1)
	v_pk_add_f32 v[8:9], v[4:5], v[8:9]
	v_pk_add_f32 v[6:7], v[6:7], v[10:11]
	s_waitcnt vmcnt(0)
	v_pk_add_f32 v[10:11], v[0:1], v[12:13]
	v_mul_f32_e32 v0, v9, v9
	v_fmac_f32_e32 v0, v8, v8
	v_fmac_f32_e32 v0, v6, v6
	v_fmac_f32_e32 v0, v7, v7
	v_fmac_f32_e32 v0, v10, v10
	v_pk_add_f32 v[2:3], v[2:3], v[14:15]
	v_fmac_f32_e32 v0, v11, v11
	v_fmac_f32_e32 v0, v2, v2
	v_fmac_f32_e32 v0, v3, v3
	v_add_f32_e32 v0, v19, v0
	v_mov_b32_e32 v1, v0
	s_nop 1
	v_permlane16_swap_b32 v0, v1
	v_cvt_pk_f16_f32 v5, v2, v3
	v_cvt_pk_f16_f32 v3, v6, v7
	v_cvt_pk_f16_f32 v4, v10, v11
	v_cvt_pk_f16_f32 v2, v8, v9
	s_waitcnt lgkmcnt(0)
	v_add_f32_e32 v0, v0, v1
	v_mov_b32_e32 v1, v0
	s_nop 1
	v_permlane32_swap_b32 v0, v1
	global_store_dwordx4 v[28:29], v[2:5], off offset:256
	s_and_saveexec_b64 s[22:23], s[6:7]
	s_cbranch_execz .LBB0_414
	v_lshl_add_u64 v[2:3], v[16:17], 2, s[14:15]
	s_waitcnt lgkmcnt(0)
	v_add_f32_e32 v0, v0, v1
	global_atomic_add_f32 v[2:3], v0, off
	s_branch .LBB0_414

;     __device__ __forceinline__ void operator()(f32x4 (&acc)[2][2][4][2], const pg8::Unit& u, int wr, int wc, int fr, int fq) const {
;     ...
;                 const int row = row0 + ai * 128 + m * 16;
;                 float ss = 0.f;
; #pragma unroll
;                 for (int bj = 0; bj < 2; ++bj) {
;                     const int c = col0 + bj * 128;
;                     const h16x8 r8 = *(const h16x8*)(res16 + (size_t)row * D + c);
;                     f32x4 v0 = acc[ai][bj][m][0], v1 = acc[ai][bj][m][1];
; #pragma unroll
;                     for (int j = 0; j < 4; ++j) { v0[j] += (float)r8[j]; v1[j] += (float)r8[4 + j]; }
;                     acc[ai][bj][m][0] = v0; acc[ai][bj][m][1] = v1;
;                     ss += v0[0] * v0[0] + v0[1] * v0[1] + v0[2] * v0[2] + v0[3] * v0[3] + v1[0] * v1[0] + v1[1] * v1[1] + v1[2] * v1[2] + v1[3] * v1[3];
;                 }
;                 ss += __shfl_xor(ss, 16); ss += __shfl_xor(ss, 32);
;                 if (fq == 0) atomicAdd(rowss + row, ss);
.LBB0_575:
	s_lshl_b32 s1, s0, 8
	v_lshlrev_b32_e32 v139, 3, v137
	s_add_i32 s1, s1, s43
	v_or_b32_e32 v138, s1, v147
	v_lshl_or_b32 v139, s47, 8, v139
	v_or_b32_e32 v140, s44, v139
	v_ashrrev_i32_e32 v139, 31, v138
	v_lshlrev_b64 v[142:143], 11, v[138:139]
	v_lshl_add_u64 v[142:143], s[10:11], 0, v[142:143]
	v_ashrrev_i32_e32 v141, 31, v140
	v_lshl_add_u64 v[148:149], v[140:141], 1, v[142:143]
	s_barrier
	global_load_dwordx4 v[142:145], v[148:149], off
	s_nop 0
	global_load_dwordx4 v[148:151], v[148:149], off offset:256
	v_xor_b32_e32 v147, 16, v129
	v_cmp_lt_i32_e32 vcc, v147, v135
	s_waitcnt vmcnt(0)
	v_cvt_f32_f16_e32 v152, v142
	v_cvt_f32_f16_sdwa v153, v142 dst_sel:DWORD dst_unused:UNUSED_PAD src0_sel:WORD_1
	v_cvt_f32_f16_e32 v154, v144
	v_cvt_f32_f16_sdwa v155, v144 dst_sel:DWORD dst_unused:UNUSED_PAD src0_sel:WORD_1
	v_cvt_f32_f16_e32 v158, v148
	v_cvt_f32_f16_sdwa v159, v148 dst_sel:DWORD dst_unused:UNUSED_PAD src0_sel:WORD_1
	v_cvt_f32_f16_e32 v156, v143
	v_cvt_f32_f16_sdwa v157, v143 dst_sel:DWORD dst_unused:UNUSED_PAD src0_sel:WORD_1
	v_cvt_f32_f16_e32 v160, v150
	v_cvt_f32_f16_sdwa v161, v150 dst_sel:DWORD dst_unused:UNUSED_PAD src0_sel:WORD_1
	v_cvt_f32_f16_e32 v148, v149
	v_cvt_f32_f16_sdwa v149, v149 dst_sel:DWORD dst_unused:UNUSED_PAD src0_sel:WORD_1
	v_cvt_f32_f16_e32 v144, v145
	v_cvt_f32_f16_sdwa v145, v145 dst_sel:DWORD dst_unused:UNUSED_PAD src0_sel:WORD_1
	v_pk_add_f32 v[142:143], v[124:125], v[152:153]
	v_pk_add_f32 v[124:125], v[120:121], v[154:155]
	v_pk_add_f32 v[120:121], v[116:117], v[158:159]
	v_cvt_f32_f16_e32 v150, v151
	v_cvt_f32_f16_sdwa v151, v151 dst_sel:DWORD dst_unused:UNUSED_PAD src0_sel:WORD_1
	v_pk_add_f32 v[126:127], v[126:127], v[156:157]
	v_pk_add_f32 v[116:117], v[112:113], v[160:161]
	v_pk_add_f32 v[118:119], v[118:119], v[148:149]
	v_pk_mul_f32 v[112:113], v[142:143], v[142:143]
	v_pk_mul_f32 v[152:153], v[120:121], v[120:121]
	v_pk_add_f32 v[122:123], v[122:123], v[144:145]
	v_pk_mul_f32 v[144:145], v[126:127], v[126:127]
	v_pk_mul_f32 v[154:155], v[118:119], v[118:119]
	v_add_f32_e32 v152, v152, v153
	v_add_f32_e32 v112, v112, v113
	v_add_f32_e32 v113, v154, v152
	v_add_f32_e32 v112, v144, v112
	v_pk_mul_f32 v[148:149], v[124:125], v[124:125]
	v_pk_mul_f32 v[156:157], v[116:117], v[116:117]
	v_add_f32_e32 v113, v155, v113
	v_add_f32_e32 v112, v145, v112
	v_pk_add_f32 v[114:115], v[114:115], v[150:151]
	v_add_f32_e32 v113, v156, v113
	v_add_f32_e32 v112, v148, v112
	v_pk_mul_f32 v[150:151], v[122:123], v[122:123]
	v_pk_mul_f32 v[158:159], v[114:115], v[114:115]
	v_add_f32_e32 v113, v157, v113
	v_add_f32_e32 v112, v149, v112
	v_add_f32_e32 v113, v158, v113
	v_add_f32_e32 v112, v150, v112
	v_cndmask_b32_e32 v147, v129, v147, vcc
	v_add_f32_e32 v113, v159, v113
	v_add_f32_e32 v112, v151, v112
	v_lshlrev_b32_e32 v147, 2, v147
	v_add_f32_e32 v112, v112, v113
	v_mov_b32_e32 v113, v112
	s_nop 1
	v_permlane16_swap_b32 v112, v113
	v_xor_b32_e32 v144, 32, v129
	v_cmp_lt_i32_e32 vcc, v144, v135
	s_nop 1
	v_cndmask_b32_e32 v144, v129, v144, vcc
	v_lshlrev_b32_e32 v166, 2, v144
	s_waitcnt lgkmcnt(0)
	v_add_f32_e32 v144, v112, v113
	v_mov_b32_e32 v145, v144
	s_nop 1
	v_permlane32_swap_b32 v144, v145
	v_cmp_eq_u32_e32 vcc, 0, v137
	v_lshl_add_u64 v[112:113], v[138:139], 2, s[14:15]
	s_and_saveexec_b64 s[4:5], vcc
	v_readlane_b32 s48, v253, 20
	v_readlane_b32 s60, v253, 32
	v_readlane_b32 s61, v253, 33
	v_readlane_b32 s62, v253, 34
	v_readlane_b32 s63, v253, 35
	v_readlane_b32 s49, v253, 21
	v_readlane_b32 s50, v253, 22
	v_readlane_b32 s51, v253, 23
	v_readlane_b32 s52, v253, 24
	v_readlane_b32 s53, v253, 25
	v_readlane_b32 s54, v253, 26
	v_readlane_b32 s55, v253, 27
	v_readlane_b32 s56, v253, 28
	v_readlane_b32 s57, v253, 29
	v_readlane_b32 s58, v253, 30
	v_readlane_b32 s59, v253, 31
	s_cbranch_execz .LBB0_577
	s_waitcnt lgkmcnt(0)
	v_add_f32_e32 v137, v144, v145
	global_atomic_add_f32 v[112:113], v137, off
.LBB0_577:
	s_or_b64 exec, exec, s[4:5]
	v_or_b32_e32 v144, 16, v138
	s_waitcnt lgkmcnt(0)
	v_ashrrev_i32_e32 v145, 31, v144
	v_lshlrev_b64 v[148:149], 11, v[144:145]
	v_lshl_add_u64 v[148:149], s[10:11], 0, v[148:149]
	v_lshl_add_u64 v[152:153], v[140:141], 1, v[148:149]
	global_load_dwordx4 v[148:151], v[152:153], off
	s_nop 0
	global_load_dwordx4 v[152:155], v[152:153], off offset:256
	s_waitcnt vmcnt(1)
	v_cvt_f32_f16_e32 v156, v148
	v_cvt_f32_f16_sdwa v157, v148 dst_sel:DWORD dst_unused:UNUSED_PAD src0_sel:WORD_1
	s_waitcnt vmcnt(0)
	v_cvt_f32_f16_e32 v162, v152
	v_cvt_f32_f16_sdwa v163, v152 dst_sel:DWORD dst_unused:UNUSED_PAD src0_sel:WORD_1
	v_cvt_f32_f16_e32 v158, v150
	v_cvt_f32_f16_sdwa v159, v150 dst_sel:DWORD dst_unused:UNUSED_PAD src0_sel:WORD_1
	v_cvt_f32_f16_e32 v160, v149
	v_cvt_f32_f16_sdwa v161, v149 dst_sel:DWORD dst_unused:UNUSED_PAD src0_sel:WORD_1
	v_cvt_f32_f16_e32 v152, v153
	v_cvt_f32_f16_sdwa v153, v153 dst_sel:DWORD dst_unused:UNUSED_PAD src0_sel:WORD_1
	v_cvt_f32_f16_e32 v150, v151
	v_cvt_f32_f16_sdwa v151, v151 dst_sel:DWORD dst_unused:UNUSED_PAD src0_sel:WORD_1
	v_cvt_f32_f16_e32 v164, v154
	v_cvt_f32_f16_sdwa v165, v154 dst_sel:DWORD dst_unused:UNUSED_PAD src0_sel:WORD_1
	v_pk_add_f32 v[148:149], v[108:109], v[156:157]
	v_pk_add_f32 v[100:101], v[100:101], v[162:163]
	v_cvt_f32_f16_e32 v154, v155
	v_cvt_f32_f16_sdwa v155, v155 dst_sel:DWORD dst_unused:UNUSED_PAD src0_sel:WORD_1
	v_pk_add_f32 v[108:109], v[104:105], v[158:159]
	v_pk_add_f32 v[110:111], v[110:111], v[160:161]
	v_pk_add_f32 v[102:103], v[102:103], v[152:153]
	v_pk_mul_f32 v[104:105], v[148:149], v[148:149]
	v_pk_mul_f32 v[156:157], v[100:101], v[100:101]
	v_pk_add_f32 v[106:107], v[106:107], v[150:151]
	v_pk_mul_f32 v[150:151], v[110:111], v[110:111]
	v_pk_mul_f32 v[158:159], v[102:103], v[102:103]
	v_add_f32_e32 v137, v156, v157
	v_add_f32_e32 v104, v104, v105
	v_pk_add_f32 v[96:97], v[96:97], v[164:165]
	v_add_f32_e32 v105, v158, v137
	v_add_f32_e32 v104, v150, v104
	v_pk_mul_f32 v[152:153], v[108:109], v[108:109]
	v_pk_mul_f32 v[160:161], v[96:97], v[96:97]
	v_add_f32_e32 v105, v159, v105
	v_add_f32_e32 v104, v151, v104
	v_pk_add_f32 v[98:99], v[98:99], v[154:155]
	v_add_f32_e32 v105, v160, v105
	v_add_f32_e32 v104, v152, v104
	v_pk_mul_f32 v[154:155], v[106:107], v[106:107]
	v_pk_mul_f32 v[162:163], v[98:99], v[98:99]
	v_add_f32_e32 v105, v161, v105
	v_add_f32_e32 v104, v153, v104
	v_add_f32_e32 v105, v162, v105
	v_add_f32_e32 v104, v154, v104
	v_add_f32_e32 v105, v163, v105
	v_add_f32_e32 v104, v155, v104
	v_add_f32_e32 v104, v104, v105
	v_mov_b32_e32 v105, v104
	s_nop 1
	v_permlane16_swap_b32 v104, v105
	v_lshl_add_u64 v[152:153], v[144:145], 2, s[14:15]
	s_waitcnt lgkmcnt(0)
	v_add_f32_e32 v104, v104, v105
	v_mov_b32_e32 v105, v104
	s_nop 1
	v_permlane32_swap_b32 v104, v105
	s_and_saveexec_b64 s[4:5], vcc
	s_cbranch_execz .LBB0_579
	s_waitcnt lgkmcnt(0)
	v_add_f32_e32 v104, v104, v105
	global_atomic_add_f32 v[152:153], v104, off
;     __device__ __forceinline__ void operator()(f32x4 (&acc)[2][2][4][2], const pg8::Unit& u, int wr, int wc, int fr, int fq) const {
;     ...
;                 const int row = row0 + ai * 128 + m * 16;
;                 float ss = 0.f;
; #pragma unroll
;                 for (int bj = 0; bj < 2; ++bj) {
;                     const int c = col0 + bj * 128;
;                     const h16x8 r8 = *(const h16x8*)(res16 + (size_t)row * D + c);
;                     f32x4 v0 = acc[ai][bj][m][0], v1 = acc[ai][bj][m][1];
; #pragma unroll
;                     for (int j = 0; j < 4; ++j) { v0[j] += (float)r8[j]; v1[j] += (float)r8[4 + j]; }
;                     acc[ai][bj][m][0] = v0; acc[ai][bj][m][1] = v1;
;                     ss += v0[0] * v0[0] + v0[1] * v0[1] + v0[2] * v0[2] + v0[3] * v0[3] + v1[0] * v1[0] + v1[1] * v1[1] + v1[2] * v1[2] + v1[3] * v1[3];
;                 }
;                 ss += __shfl_xor(ss, 16); ss += __shfl_xor(ss, 32);
;                 if (fq == 0) atomicAdd(rowss + row, ss);
.LBB0_579:
	s_or_b64 exec, exec, s[4:5]
	v_or_b32_e32 v104, 32, v138
	s_waitcnt lgkmcnt(0)
	v_ashrrev_i32_e32 v105, 31, v104
	v_lshlrev_b64 v[150:151], 11, v[104:105]
	v_lshl_add_u64 v[150:151], s[10:11], 0, v[150:151]
	v_lshl_add_u64 v[150:151], v[140:141], 1, v[150:151]
	global_load_dwordx4 v[154:157], v[150:151], off
	global_load_dwordx4 v[158:161], v[150:151], off offset:256
	s_waitcnt vmcnt(1)
	v_cvt_f32_f16_e32 v150, v154
	v_cvt_f32_f16_sdwa v151, v154 dst_sel:DWORD dst_unused:UNUSED_PAD src0_sel:WORD_1
	s_waitcnt vmcnt(0)
	v_cvt_f32_f16_e32 v164, v158
	v_cvt_f32_f16_sdwa v165, v158 dst_sel:DWORD dst_unused:UNUSED_PAD src0_sel:WORD_1
	v_cvt_f32_f16_e32 v162, v156
	v_cvt_f32_f16_sdwa v163, v156 dst_sel:DWORD dst_unused:UNUSED_PAD src0_sel:WORD_1
	v_cvt_f32_f16_e32 v154, v155
	v_cvt_f32_f16_sdwa v155, v155 dst_sel:DWORD dst_unused:UNUSED_PAD src0_sel:WORD_1
	v_cvt_f32_f16_e32 v168, v160
	v_cvt_f32_f16_sdwa v169, v160 dst_sel:DWORD dst_unused:UNUSED_PAD src0_sel:WORD_1
	v_cvt_f32_f16_e32 v158, v159
	v_cvt_f32_f16_sdwa v159, v159 dst_sel:DWORD dst_unused:UNUSED_PAD src0_sel:WORD_1
	v_cvt_f32_f16_e32 v160, v161
	v_cvt_f32_f16_sdwa v161, v161 dst_sel:DWORD dst_unused:UNUSED_PAD src0_sel:WORD_1
	v_cvt_f32_f16_e32 v156, v157
	v_cvt_f32_f16_sdwa v157, v157 dst_sel:DWORD dst_unused:UNUSED_PAD src0_sel:WORD_1
	v_pk_add_f32 v[150:151], v[92:93], v[150:151]
	v_pk_add_f32 v[84:85], v[84:85], v[164:165]
	v_pk_add_f32 v[92:93], v[88:89], v[162:163]
	v_pk_add_f32 v[94:95], v[94:95], v[154:155]
	v_pk_add_f32 v[86:87], v[86:87], v[158:159]
	v_pk_add_f32 v[82:83], v[82:83], v[160:161]
	v_pk_mul_f32 v[88:89], v[150:151], v[150:151]
	v_pk_mul_f32 v[160:161], v[84:85], v[84:85]
	v_pk_mul_f32 v[154:155], v[94:95], v[94:95]
	v_pk_mul_f32 v[162:163], v[86:87], v[86:87]
	v_add_f32_e32 v137, v160, v161
	v_add_f32_e32 v88, v88, v89
	v_pk_add_f32 v[80:81], v[80:81], v[168:169]
	v_add_f32_e32 v89, v162, v137
	v_add_f32_e32 v88, v154, v88
	v_pk_add_f32 v[90:91], v[90:91], v[156:157]
	v_pk_mul_f32 v[156:157], v[92:93], v[92:93]
	v_pk_mul_f32 v[164:165], v[80:81], v[80:81]
	v_add_f32_e32 v89, v163, v89
	v_add_f32_e32 v88, v155, v88
	v_add_f32_e32 v89, v164, v89
	v_add_f32_e32 v88, v156, v88
	v_pk_mul_f32 v[158:159], v[90:91], v[90:91]
	v_pk_mul_f32 v[168:169], v[82:83], v[82:83]
	v_add_f32_e32 v89, v165, v89
	v_add_f32_e32 v88, v157, v88
	v_add_f32_e32 v89, v168, v89
	v_add_f32_e32 v88, v158, v88
	v_add_f32_e32 v89, v169, v89
	v_add_f32_e32 v88, v159, v88
	v_add_f32_e32 v88, v88, v89
	v_mov_b32_e32 v89, v88
	s_nop 1
	v_permlane16_swap_b32 v88, v89
	v_lshl_add_u64 v[156:157], v[104:105], 2, s[14:15]
	s_waitcnt lgkmcnt(0)
	v_add_f32_e32 v88, v88, v89
	v_mov_b32_e32 v89, v88
	s_nop 1
	v_permlane32_swap_b32 v88, v89
	s_and_saveexec_b64 s[4:5], vcc
	s_cbranch_execz .LBB0_581
	s_waitcnt lgkmcnt(0)
	v_add_f32_e32 v88, v88, v89
	global_atomic_add_f32 v[156:157], v88, off
.LBB0_581:
	s_or_b64 exec, exec, s[4:5]
	v_or_b32_e32 v88, 48, v138
	s_waitcnt lgkmcnt(0)
	v_ashrrev_i32_e32 v89, 31, v88
	v_lshlrev_b64 v[154:155], 11, v[88:89]
	v_lshl_add_u64 v[154:155], s[10:11], 0, v[154:155]
	v_lshl_add_u64 v[154:155], v[140:141], 1, v[154:155]
	global_load_dwordx4 v[158:161], v[154:155], off
	global_load_dwordx4 v[162:165], v[154:155], off offset:256
	s_waitcnt vmcnt(1)
	v_cvt_f32_f16_e32 v154, v158
	v_cvt_f32_f16_sdwa v155, v158 dst_sel:DWORD dst_unused:UNUSED_PAD src0_sel:WORD_1
	s_waitcnt vmcnt(0)
	v_cvt_f32_f16_e32 v170, v162
	v_cvt_f32_f16_sdwa v171, v162 dst_sel:DWORD dst_unused:UNUSED_PAD src0_sel:WORD_1
	v_cvt_f32_f16_e32 v168, v160
	v_cvt_f32_f16_sdwa v169, v160 dst_sel:DWORD dst_unused:UNUSED_PAD src0_sel:WORD_1
	v_cvt_f32_f16_e32 v158, v159
	v_cvt_f32_f16_sdwa v159, v159 dst_sel:DWORD dst_unused:UNUSED_PAD src0_sel:WORD_1
	v_cvt_f32_f16_e32 v172, v164
	v_cvt_f32_f16_sdwa v173, v164 dst_sel:DWORD dst_unused:UNUSED_PAD src0_sel:WORD_1
	v_cvt_f32_f16_e32 v162, v163
	v_cvt_f32_f16_sdwa v163, v163 dst_sel:DWORD dst_unused:UNUSED_PAD src0_sel:WORD_1
	v_cvt_f32_f16_e32 v164, v165
	v_cvt_f32_f16_sdwa v165, v165 dst_sel:DWORD dst_unused:UNUSED_PAD src0_sel:WORD_1
	v_cvt_f32_f16_e32 v160, v161
	v_cvt_f32_f16_sdwa v161, v161 dst_sel:DWORD dst_unused:UNUSED_PAD src0_sel:WORD_1
	v_pk_add_f32 v[154:155], v[76:77], v[154:155]
	v_pk_add_f32 v[68:69], v[68:69], v[170:171]
	v_pk_add_f32 v[76:77], v[72:73], v[168:169]
	v_pk_add_f32 v[78:79], v[78:79], v[158:159]
	v_pk_add_f32 v[70:71], v[70:71], v[162:163]
	v_pk_add_f32 v[66:67], v[66:67], v[164:165]
	v_pk_mul_f32 v[72:73], v[154:155], v[154:155]
	v_pk_mul_f32 v[164:165], v[68:69], v[68:69]
	v_pk_mul_f32 v[158:159], v[78:79], v[78:79]
	v_pk_mul_f32 v[168:169], v[70:71], v[70:71]
	v_add_f32_e32 v137, v164, v165
	v_add_f32_e32 v72, v72, v73
	v_pk_add_f32 v[64:65], v[64:65], v[172:173]
	v_add_f32_e32 v73, v168, v137
	v_add_f32_e32 v72, v158, v72
	v_pk_add_f32 v[74:75], v[74:75], v[160:161]
	v_pk_mul_f32 v[160:161], v[76:77], v[76:77]
	v_pk_mul_f32 v[170:171], v[64:65], v[64:65]
	v_add_f32_e32 v73, v169, v73
	v_add_f32_e32 v72, v159, v72
	v_add_f32_e32 v73, v170, v73
	v_add_f32_e32 v72, v160, v72
	v_pk_mul_f32 v[162:163], v[74:75], v[74:75]
	v_pk_mul_f32 v[172:173], v[66:67], v[66:67]
	v_add_f32_e32 v73, v171, v73
	v_add_f32_e32 v72, v161, v72
	v_add_f32_e32 v73, v172, v73
	v_add_f32_e32 v72, v162, v72
	v_add_f32_e32 v73, v173, v73
	v_add_f32_e32 v72, v163, v72
	v_add_f32_e32 v72, v72, v73
	v_mov_b32_e32 v73, v72
	s_nop 1
	v_permlane16_swap_b32 v72, v73
	v_lshl_add_u64 v[160:161], v[88:89], 2, s[14:15]
	s_waitcnt lgkmcnt(0)
	v_add_f32_e32 v72, v72, v73
	v_mov_b32_e32 v73, v72
	s_nop 1
	v_permlane32_swap_b32 v72, v73
	s_and_saveexec_b64 s[4:5], vcc
	s_cbranch_execz .LBB0_583
	s_waitcnt lgkmcnt(0)
	v_add_f32_e32 v72, v72, v73
	global_atomic_add_f32 v[160:161], v72, off
;     __device__ __forceinline__ void operator()(f32x4 (&acc)[2][2][4][2], const pg8::Unit& u, int wr, int wc, int fr, int fq) const {
;     ...
;                 const int row = row0 + ai * 128 + m * 16;
;                 float ss = 0.f;
; #pragma unroll
;                 for (int bj = 0; bj < 2; ++bj) {
;                     const int c = col0 + bj * 128;
;                     const h16x8 r8 = *(const h16x8*)(res16 + (size_t)row * D + c);
;                     f32x4 v0 = acc[ai][bj][m][0], v1 = acc[ai][bj][m][1];
; #pragma unroll
;                     for (int j = 0; j < 4; ++j) { v0[j] += (float)r8[j]; v1[j] += (float)r8[4 + j]; }
;                     acc[ai][bj][m][0] = v0; acc[ai][bj][m][1] = v1;
;                     ss += v0[0] * v0[0] + v0[1] * v0[1] + v0[2] * v0[2] + v0[3] * v0[3] + v1[0] * v1[0] + v1[1] * v1[1] + v1[2] * v1[2] + v1[3] * v1[3];
;                 }
;                 ss += __shfl_xor(ss, 16); ss += __shfl_xor(ss, 32);
;                 if (fq == 0) atomicAdd(rowss + row, ss);
.LBB0_583:
	s_or_b64 exec, exec, s[4:5]
	v_add_u32_e32 v72, 0x80, v138
	s_waitcnt lgkmcnt(0)
	v_ashrrev_i32_e32 v73, 31, v72
	v_lshlrev_b64 v[158:159], 11, v[72:73]
	v_lshl_add_u64 v[158:159], s[10:11], 0, v[158:159]
	v_lshl_add_u64 v[158:159], v[140:141], 1, v[158:159]
	global_load_dwordx4 v[162:165], v[158:159], off
	global_load_dwordx4 v[168:171], v[158:159], off offset:256
	s_waitcnt vmcnt(1)
	v_cvt_f32_f16_e32 v158, v162
	v_cvt_f32_f16_sdwa v159, v162 dst_sel:DWORD dst_unused:UNUSED_PAD src0_sel:WORD_1
	s_waitcnt vmcnt(0)
	v_cvt_f32_f16_e32 v174, v168
	v_cvt_f32_f16_sdwa v175, v168 dst_sel:DWORD dst_unused:UNUSED_PAD src0_sel:WORD_1
	v_cvt_f32_f16_e32 v172, v164
	v_cvt_f32_f16_sdwa v173, v164 dst_sel:DWORD dst_unused:UNUSED_PAD src0_sel:WORD_1
	v_cvt_f32_f16_e32 v162, v163
	v_cvt_f32_f16_sdwa v163, v163 dst_sel:DWORD dst_unused:UNUSED_PAD src0_sel:WORD_1
	v_cvt_f32_f16_e32 v176, v170
	v_cvt_f32_f16_sdwa v177, v170 dst_sel:DWORD dst_unused:UNUSED_PAD src0_sel:WORD_1
	v_cvt_f32_f16_e32 v168, v169
	v_cvt_f32_f16_sdwa v169, v169 dst_sel:DWORD dst_unused:UNUSED_PAD src0_sel:WORD_1
	v_cvt_f32_f16_e32 v170, v171
	v_cvt_f32_f16_sdwa v171, v171 dst_sel:DWORD dst_unused:UNUSED_PAD src0_sel:WORD_1
	v_cvt_f32_f16_e32 v164, v165
	v_cvt_f32_f16_sdwa v165, v165 dst_sel:DWORD dst_unused:UNUSED_PAD src0_sel:WORD_1
	v_pk_add_f32 v[158:159], v[60:61], v[158:159]
	v_pk_add_f32 v[52:53], v[52:53], v[174:175]
	v_pk_add_f32 v[60:61], v[56:57], v[172:173]
	v_pk_add_f32 v[62:63], v[62:63], v[162:163]
	v_pk_add_f32 v[54:55], v[54:55], v[168:169]
	v_pk_add_f32 v[50:51], v[50:51], v[170:171]
	v_pk_mul_f32 v[56:57], v[158:159], v[158:159]
	v_pk_mul_f32 v[170:171], v[52:53], v[52:53]
	v_pk_mul_f32 v[162:163], v[62:63], v[62:63]
	v_pk_mul_f32 v[172:173], v[54:55], v[54:55]
	v_add_f32_e32 v137, v170, v171
	v_add_f32_e32 v56, v56, v57
	v_pk_add_f32 v[48:49], v[48:49], v[176:177]
	v_add_f32_e32 v57, v172, v137
	v_add_f32_e32 v56, v162, v56
	v_pk_add_f32 v[58:59], v[58:59], v[164:165]
	v_pk_mul_f32 v[164:165], v[60:61], v[60:61]
	v_pk_mul_f32 v[174:175], v[48:49], v[48:49]
	v_add_f32_e32 v57, v173, v57
	v_add_f32_e32 v56, v163, v56
	v_add_f32_e32 v57, v174, v57
	v_add_f32_e32 v56, v164, v56
	v_pk_mul_f32 v[168:169], v[58:59], v[58:59]
	v_pk_mul_f32 v[176:177], v[50:51], v[50:51]
	v_add_f32_e32 v57, v175, v57
	v_add_f32_e32 v56, v165, v56
	v_add_f32_e32 v57, v176, v57
	v_add_f32_e32 v56, v168, v56
	v_add_f32_e32 v57, v177, v57
	v_add_f32_e32 v56, v169, v56
	v_add_f32_e32 v56, v56, v57
	v_mov_b32_e32 v57, v56
	s_nop 1
	v_permlane16_swap_b32 v56, v57
	s_waitcnt lgkmcnt(0)
	v_add_f32_e32 v56, v56, v57
	v_mov_b32_e32 v57, v56
	s_nop 1
	v_permlane32_swap_b32 v56, v57
	s_and_saveexec_b64 s[4:5], vcc
	s_cbranch_execz .LBB0_585
	v_lshl_add_u64 v[162:163], v[72:73], 2, s[14:15]
	s_waitcnt lgkmcnt(0)
	v_add_f32_e32 v56, v56, v57
	global_atomic_add_f32 v[162:163], v56, off
.LBB0_585:
	s_or_b64 exec, exec, s[4:5]
	v_add_u32_e32 v56, 0x90, v138
	s_waitcnt lgkmcnt(0)
	v_ashrrev_i32_e32 v57, 31, v56
	v_lshlrev_b64 v[162:163], 11, v[56:57]
	v_lshl_add_u64 v[162:163], s[10:11], 0, v[162:163]
	v_lshl_add_u64 v[168:169], v[140:141], 1, v[162:163]
	global_load_dwordx4 v[162:165], v[168:169], off
	s_nop 0
	global_load_dwordx4 v[168:171], v[168:169], off offset:256
	s_waitcnt vmcnt(1)
	v_cvt_f32_f16_e32 v172, v162
	v_cvt_f32_f16_sdwa v173, v162 dst_sel:DWORD dst_unused:UNUSED_PAD src0_sel:WORD_1
	s_waitcnt vmcnt(0)
	v_cvt_f32_f16_e32 v178, v168
	v_cvt_f32_f16_sdwa v179, v168 dst_sel:DWORD dst_unused:UNUSED_PAD src0_sel:WORD_1
	v_cvt_f32_f16_e32 v174, v164
	v_cvt_f32_f16_sdwa v175, v164 dst_sel:DWORD dst_unused:UNUSED_PAD src0_sel:WORD_1
	v_cvt_f32_f16_e32 v176, v163
	v_cvt_f32_f16_sdwa v177, v163 dst_sel:DWORD dst_unused:UNUSED_PAD src0_sel:WORD_1
	v_cvt_f32_f16_e32 v168, v169
	v_cvt_f32_f16_sdwa v169, v169 dst_sel:DWORD dst_unused:UNUSED_PAD src0_sel:WORD_1
	v_cvt_f32_f16_e32 v164, v165
	v_cvt_f32_f16_sdwa v165, v165 dst_sel:DWORD dst_unused:UNUSED_PAD src0_sel:WORD_1
	v_cvt_f32_f16_e32 v180, v170
	v_cvt_f32_f16_sdwa v181, v170 dst_sel:DWORD dst_unused:UNUSED_PAD src0_sel:WORD_1
	v_pk_add_f32 v[162:163], v[44:45], v[172:173]
	v_pk_add_f32 v[36:37], v[36:37], v[178:179]
	v_cvt_f32_f16_e32 v170, v171
	v_cvt_f32_f16_sdwa v171, v171 dst_sel:DWORD dst_unused:UNUSED_PAD src0_sel:WORD_1
	v_pk_add_f32 v[44:45], v[40:41], v[174:175]
	v_pk_add_f32 v[46:47], v[46:47], v[176:177]
	v_pk_add_f32 v[38:39], v[38:39], v[168:169]
	v_pk_mul_f32 v[40:41], v[162:163], v[162:163]
	v_pk_mul_f32 v[172:173], v[36:37], v[36:37]
	v_pk_add_f32 v[42:43], v[42:43], v[164:165]
	v_pk_mul_f32 v[164:165], v[46:47], v[46:47]
	v_pk_mul_f32 v[174:175], v[38:39], v[38:39]
	v_add_f32_e32 v137, v172, v173
	v_add_f32_e32 v40, v40, v41
	v_pk_add_f32 v[32:33], v[32:33], v[180:181]
	v_add_f32_e32 v41, v174, v137
	v_add_f32_e32 v40, v164, v40
	v_pk_mul_f32 v[168:169], v[44:45], v[44:45]
	v_pk_mul_f32 v[176:177], v[32:33], v[32:33]
	v_add_f32_e32 v41, v175, v41
	v_add_f32_e32 v40, v165, v40
	v_pk_add_f32 v[34:35], v[34:35], v[170:171]
	v_add_f32_e32 v41, v176, v41
	v_add_f32_e32 v40, v168, v40
	v_pk_mul_f32 v[170:171], v[42:43], v[42:43]
	v_pk_mul_f32 v[178:179], v[34:35], v[34:35]
	v_add_f32_e32 v41, v177, v41
	v_add_f32_e32 v40, v169, v40
	v_add_f32_e32 v41, v178, v41
	v_add_f32_e32 v40, v170, v40
	v_add_f32_e32 v41, v179, v41
	v_add_f32_e32 v40, v171, v40
	v_add_f32_e32 v40, v40, v41
	v_mov_b32_e32 v41, v40
	s_nop 1
	v_permlane16_swap_b32 v40, v41
	s_waitcnt lgkmcnt(0)
	v_add_f32_e32 v40, v40, v41
	v_mov_b32_e32 v41, v40
	s_nop 1
	v_permlane32_swap_b32 v40, v41
	s_and_saveexec_b64 s[4:5], vcc
	s_cbranch_execz .LBB0_587
	v_lshl_add_u64 v[164:165], v[56:57], 2, s[14:15]
	s_waitcnt lgkmcnt(0)
	v_add_f32_e32 v40, v40, v41
	global_atomic_add_f32 v[164:165], v40, off
;     __device__ __forceinline__ void operator()(f32x4 (&acc)[2][2][4][2], const pg8::Unit& u, int wr, int wc, int fr, int fq) const {
;     ...
;                 const int row = row0 + ai * 128 + m * 16;
;                 float ss = 0.f;
; #pragma unroll
;                 for (int bj = 0; bj < 2; ++bj) {
;                     const int c = col0 + bj * 128;
;                     const h16x8 r8 = *(const h16x8*)(res16 + (size_t)row * D + c);
;                     f32x4 v0 = acc[ai][bj][m][0], v1 = acc[ai][bj][m][1];
; #pragma unroll
;                     for (int j = 0; j < 4; ++j) { v0[j] += (float)r8[j]; v1[j] += (float)r8[4 + j]; }
;                     acc[ai][bj][m][0] = v0; acc[ai][bj][m][1] = v1;
;                     ss += v0[0] * v0[0] + v0[1] * v0[1] + v0[2] * v0[2] + v0[3] * v0[3] + v1[0] * v1[0] + v1[1] * v1[1] + v1[2] * v1[2] + v1[3] * v1[3];
;                 }
;                 ss += __shfl_xor(ss, 16); ss += __shfl_xor(ss, 32);
;                 if (fq == 0) atomicAdd(rowss + row, ss);
.LBB0_587:
	s_or_b64 exec, exec, s[4:5]
	v_add_u32_e32 v40, 0xa0, v138
	s_waitcnt lgkmcnt(0)
	v_ashrrev_i32_e32 v41, 31, v40
	v_lshlrev_b64 v[164:165], 11, v[40:41]
	v_lshl_add_u64 v[164:165], s[10:11], 0, v[164:165]
	v_lshl_add_u64 v[164:165], v[140:141], 1, v[164:165]
	global_load_dwordx4 v[168:171], v[164:165], off
	global_load_dwordx4 v[172:175], v[164:165], off offset:256
	s_waitcnt vmcnt(1)
	v_cvt_f32_f16_e32 v164, v168
	v_cvt_f32_f16_sdwa v165, v168 dst_sel:DWORD dst_unused:UNUSED_PAD src0_sel:WORD_1
	s_waitcnt vmcnt(0)
	v_cvt_f32_f16_e32 v178, v172
	v_cvt_f32_f16_sdwa v179, v172 dst_sel:DWORD dst_unused:UNUSED_PAD src0_sel:WORD_1
	v_cvt_f32_f16_e32 v176, v170
	v_cvt_f32_f16_sdwa v177, v170 dst_sel:DWORD dst_unused:UNUSED_PAD src0_sel:WORD_1
	v_cvt_f32_f16_e32 v168, v169
	v_cvt_f32_f16_sdwa v169, v169 dst_sel:DWORD dst_unused:UNUSED_PAD src0_sel:WORD_1
	v_cvt_f32_f16_e32 v180, v174
	v_cvt_f32_f16_sdwa v181, v174 dst_sel:DWORD dst_unused:UNUSED_PAD src0_sel:WORD_1
	v_cvt_f32_f16_e32 v172, v173
	v_cvt_f32_f16_sdwa v173, v173 dst_sel:DWORD dst_unused:UNUSED_PAD src0_sel:WORD_1
	v_cvt_f32_f16_e32 v174, v175
	v_cvt_f32_f16_sdwa v175, v175 dst_sel:DWORD dst_unused:UNUSED_PAD src0_sel:WORD_1
	v_cvt_f32_f16_e32 v170, v171
	v_cvt_f32_f16_sdwa v171, v171 dst_sel:DWORD dst_unused:UNUSED_PAD src0_sel:WORD_1
	v_pk_add_f32 v[164:165], v[28:29], v[164:165]
	v_pk_add_f32 v[20:21], v[20:21], v[178:179]
	v_pk_add_f32 v[28:29], v[24:25], v[176:177]
	v_pk_add_f32 v[30:31], v[30:31], v[168:169]
	v_pk_add_f32 v[22:23], v[22:23], v[172:173]
	v_pk_add_f32 v[18:19], v[18:19], v[174:175]
	v_pk_mul_f32 v[24:25], v[164:165], v[164:165]
	v_pk_mul_f32 v[174:175], v[20:21], v[20:21]
	v_pk_mul_f32 v[168:169], v[30:31], v[30:31]
	v_pk_mul_f32 v[176:177], v[22:23], v[22:23]
	v_add_f32_e32 v137, v174, v175
	v_add_f32_e32 v24, v24, v25
	v_pk_add_f32 v[16:17], v[16:17], v[180:181]
	v_add_f32_e32 v25, v176, v137
	v_add_f32_e32 v24, v168, v24
	v_pk_add_f32 v[26:27], v[26:27], v[170:171]
	v_pk_mul_f32 v[170:171], v[28:29], v[28:29]
	v_pk_mul_f32 v[178:179], v[16:17], v[16:17]
	v_add_f32_e32 v25, v177, v25
	v_add_f32_e32 v24, v169, v24
	v_add_f32_e32 v25, v178, v25
	v_add_f32_e32 v24, v170, v24
	v_pk_mul_f32 v[172:173], v[26:27], v[26:27]
	v_pk_mul_f32 v[180:181], v[18:19], v[18:19]
	v_add_f32_e32 v25, v179, v25
	v_add_f32_e32 v24, v171, v24
	v_add_f32_e32 v25, v180, v25
	v_add_f32_e32 v24, v172, v24
	v_add_f32_e32 v25, v181, v25
	v_add_f32_e32 v24, v173, v24
	v_add_f32_e32 v24, v24, v25
	v_mov_b32_e32 v25, v24
	s_nop 1
	v_permlane16_swap_b32 v24, v25
	s_waitcnt lgkmcnt(0)
	v_add_f32_e32 v24, v24, v25
	v_mov_b32_e32 v25, v24
	s_nop 1
	v_permlane32_swap_b32 v24, v25
	s_and_saveexec_b64 s[4:5], vcc
	s_cbranch_execz .LBB0_589
	v_lshl_add_u64 v[168:169], v[40:41], 2, s[14:15]
	s_waitcnt lgkmcnt(0)
	v_add_f32_e32 v24, v24, v25
	global_atomic_add_f32 v[168:169], v24, off
.LBB0_589:
	s_or_b64 exec, exec, s[4:5]
	v_add_u32_e32 v24, 0xb0, v138
	s_waitcnt lgkmcnt(0)
	v_ashrrev_i32_e32 v25, 31, v24
	v_lshlrev_b64 v[168:169], 11, v[24:25]
	v_lshl_add_u64 v[168:169], s[10:11], 0, v[168:169]
	v_lshl_add_u64 v[172:173], v[140:141], 1, v[168:169]
	global_load_dwordx4 v[168:171], v[172:173], off
	s_nop 0
	global_load_dwordx4 v[172:175], v[172:173], off offset:256
	s_waitcnt vmcnt(1)
	v_cvt_f32_f16_e32 v176, v168
	v_cvt_f32_f16_sdwa v177, v168 dst_sel:DWORD dst_unused:UNUSED_PAD src0_sel:WORD_1
	s_waitcnt vmcnt(0)
	v_cvt_f32_f16_e32 v180, v172
	v_cvt_f32_f16_sdwa v181, v172 dst_sel:DWORD dst_unused:UNUSED_PAD src0_sel:WORD_1
	v_cvt_f32_f16_e32 v168, v169
	v_cvt_f32_f16_sdwa v169, v169 dst_sel:DWORD dst_unused:UNUSED_PAD src0_sel:WORD_1
	v_cvt_f32_f16_e32 v172, v173
	v_cvt_f32_f16_sdwa v173, v173 dst_sel:DWORD dst_unused:UNUSED_PAD src0_sel:WORD_1
	v_cvt_f32_f16_e32 v178, v170
	v_cvt_f32_f16_sdwa v179, v170 dst_sel:DWORD dst_unused:UNUSED_PAD src0_sel:WORD_1
	v_cvt_f32_f16_e32 v170, v171
	v_cvt_f32_f16_sdwa v171, v171 dst_sel:DWORD dst_unused:UNUSED_PAD src0_sel:WORD_1
	v_cvt_f32_f16_e32 v182, v174
	v_cvt_f32_f16_sdwa v183, v174 dst_sel:DWORD dst_unused:UNUSED_PAD src0_sel:WORD_1
	v_pk_add_f32 v[12:13], v[12:13], v[176:177]
	v_pk_add_f32 v[4:5], v[4:5], v[180:181]
	v_cvt_f32_f16_e32 v174, v175
	v_cvt_f32_f16_sdwa v175, v175 dst_sel:DWORD dst_unused:UNUSED_PAD src0_sel:WORD_1
	v_pk_add_f32 v[14:15], v[14:15], v[168:169]
	v_pk_add_f32 v[6:7], v[6:7], v[172:173]
	v_pk_mul_f32 v[168:169], v[12:13], v[12:13]
	v_pk_mul_f32 v[176:177], v[4:5], v[4:5]
	v_pk_add_f32 v[8:9], v[8:9], v[178:179]
	v_pk_add_f32 v[10:11], v[10:11], v[170:171]
	v_pk_mul_f32 v[170:171], v[14:15], v[14:15]
	v_pk_mul_f32 v[178:179], v[6:7], v[6:7]
	v_add_f32_e32 v137, v176, v177
	v_add_f32_e32 v167, v168, v169
	v_pk_add_f32 v[0:1], v[0:1], v[182:183]
	v_add_f32_e32 v137, v178, v137
	v_add_f32_e32 v167, v170, v167
	v_pk_mul_f32 v[172:173], v[8:9], v[8:9]
	v_pk_mul_f32 v[180:181], v[0:1], v[0:1]
	v_add_f32_e32 v137, v179, v137
	v_add_f32_e32 v167, v171, v167
	v_pk_add_f32 v[2:3], v[2:3], v[174:175]
	v_add_f32_e32 v137, v180, v137
	v_add_f32_e32 v167, v172, v167
	v_pk_mul_f32 v[174:175], v[10:11], v[10:11]
	v_pk_mul_f32 v[182:183], v[2:3], v[2:3]
	v_add_f32_e32 v137, v181, v137
	v_add_f32_e32 v167, v173, v167
	v_add_f32_e32 v137, v182, v137
	v_add_f32_e32 v167, v174, v167
	v_add_f32_e32 v137, v183, v137
	v_add_f32_e32 v167, v175, v167
	v_add_f32_e32 v137, v167, v137
	v_mov_b32_e32 v147, v137
	s_nop 1
	v_permlane16_swap_b32 v137, v147
	s_waitcnt lgkmcnt(0)
	v_add_f32_e32 v137, v137, v147
	v_mov_b32_e32 v147, v137
	s_nop 1
	v_permlane32_swap_b32 v137, v147
	s_and_saveexec_b64 s[4:5], vcc
	s_cbranch_execz .LBB0_591
	v_lshl_add_u64 v[166:167], v[24:25], 2, s[14:15]
	s_waitcnt lgkmcnt(0)
	v_add_f32_e32 v137, v137, v147
	global_atomic_add_f32 v[166:167], v137, off
